# K-loop head labels aligned to 64 bytes (.p2align 6, padding not executed) on top of peeled first iteration
# baseline (speedup 1.0000x reference)
; #define PG8_STAGE(bufoff, gbase, voff) do { _Pragma("unroll") for (int _i = 0; _i < 2; ++_i) \
;         __builtin_amdgcn_global_load_lds((const unsigned*)((const char*)(gbase) + (voff)[_i]), (PG8_LAS unsigned*)(lds + (bufoff) + ldsw + _i * 8192), 16, 0, 0); } while (0)
; #define PG8_LDA(dst, b, h) do { _Pragma("unroll") for (int m = 0; m < 4; ++m) _Pragma("unroll") for (int k = 0; k < 2; ++k) dst[m][k] = *(const PG8_LAS bf16x8*)(lds + PG8_SA(b, h) + aoff + m * 2048 + k * 1024); } while (0)
; #define PG8_LDB(dst, b, h) do { _Pragma("unroll") for (int n = 0; n < 2; ++n) _Pragma("unroll") for (int k = 0; k < 2; ++k) dst[n][k] = *(const PG8_LAS bf16x8*)(lds + PG8_SB(b, h) + boff + n * 2048 + k * 1024); } while (0)
; #define PG8_MMA(ai, bj, At, Bt) do { __builtin_amdgcn_s_setprio(1); _Pragma("unroll") for (int m = 0; m < 4; ++m) _Pragma("unroll") for (int n = 0; n < 2; ++n) _Pragma("unroll") for (int k = 0; k < 2; ++k) \
;         acc[ai][bj][m][n] = __builtin_amdgcn_mfma_f32_16x16x32_bf16(Bt[n][k], At[m][k], acc[ai][bj][m][n], 0, 0, 0); __builtin_amdgcn_s_setprio(0); } while (0)
; template <class Epi, class Sched, bool ALIGN_EPI = false, bool SP2 = false>
; __device__ __forceinline__ void gemm_phase(PG8_LAS unsigned char* lds, const Gemm g, const Sched& S, const Epi& E, const int tid) {
;     ...
;     for (;;) {
;         const bool has_next = S.next(ui + 1, nxt);
;         const char* nA = has_next ? (const char*)g.A + (size_t)nxt.pm * tstep : cA; const char* nB = has_next ? (const char*)g.Bt + (size_t)nxt.pn * tstep : cB;
;         for (int t = 0; t < nt; t += 2) {
;             const bool last = (t == nt - 2);
;             const char* a1 = cA + (size_t)(t + 1) * kstep;
;             const char* a2 = last ? nA : cA + (size_t)(t + 2) * kstep; const char* b2 = last ? nB : cB + (size_t)(t + 2) * kstep;
;             const char* a3 = a2 + kstep; const char* b3 = b2 + kstep;
;             if (last && has_next) S.a_ready(nxt);
;             if constexpr (SP2) {
;             PG8_LDB(B0, 0, 0); PG8_LDB(B1, 0, 1); PG8_SCHED; PG8_LDA(At, 0, 0); PG8_STAGE(PG8_SA(1, 1), a1 + hstep, voffA);
;             PG8_WAIT_V(8); PG8_WAIT_L(0); PG8_BAR; PG8_MMA(0, 0, At, B0); PG8_MMA(0, 1, At, B1); PG8_BAR; PG8_SCHED;
;             PG8_LDA(At, 0, 1); PG8_STAGE(PG8_SB(0, 0), b2, voffB); PG8_STAGE(PG8_SB(0, 1), b2 + hstep, voffB); PG8_STAGE(PG8_SA(0, 0), a2, voffA);
.LBB0_98:
	s_ashr_i32 s13, s12, 31
	s_lshl_b64 s[14:15], s[12:13], 19
	s_add_u32 s14, s27, s14
	s_addc_u32 s15, s34, s15
	s_and_b64 s[16:17], s[2:3], exec
	s_cselect_b32 s13, s15, s19
	s_cselect_b32 s45, s14, s18
	s_ashr_i32 s11, s10, 31
	s_lshl_b64 s[16:17], s[10:11], 19
	s_add_u32 s16, s24, s16
	s_addc_u32 s17, s25, s17
	s_and_b64 s[22:23], s[2:3], exec
	s_cselect_b32 s11, s17, s21
	s_cselect_b32 s46, s16, s20
	s_add_u32 s18, s18, 0x40080
	s_addc_u32 s19, s19, 0
	s_add_u32 s47, s20, 0x100
	v_mov_b32_e32 v4, 0
	s_addc_u32 s48, s21, 0
	s_mov_b32 s49, -2
	s_add_u32 s20, s18, 0xfffc0080
	s_addc_u32 s21, s19, -1
	s_add_i32 s50, 0, 0x10000
	s_cmp_eq_u32 s49, 12
	s_cselect_b32 s23, s13, s21
	s_cselect_b32 s22, s45, s20
	s_cselect_b32 s21, s11, s48
	s_cselect_b32 s20, s46, s47
	s_add_i32 s52, 0, 0x14000
	v_add_u32_e32 v132, s50, v153
	v_add_u32_e32 v148, s52, v153
	ds_read_b128 v[116:119], v132
	ds_read_b128 v[120:123], v132 offset:1024
	ds_read_b128 v[124:127], v132 offset:2048
	ds_read_b128 v[132:135], v132 offset:3072
	ds_read_b128 v[178:181], v148
	ds_read_b128 v[182:185], v148 offset:1024
	ds_read_b128 v[186:189], v148 offset:2048
	ds_read_b128 v[190:193], v148 offset:3072
	v_lshl_add_u64 v[148:149], s[18:19], 0, v[172:173]
	s_add_i32 m0, s36, 0xc000
	ds_read_b128 v[194:197], v176
	ds_read_b128 v[198:201], v176 offset:1024
	ds_read_b128 v[202:205], v176 offset:2048
	ds_read_b128 v[206:209], v176 offset:3072
	ds_read_b128 v[210:213], v176 offset:4096
	ds_read_b128 v[214:217], v176 offset:5120
	ds_read_b128 v[218:221], v176 offset:6144
	ds_read_b128 v[222:225], v176 offset:7168
	global_load_lds_dwordx4 v[148:149], off
	v_lshl_add_u64 v[148:149], s[18:19], 0, v[174:175]
	s_add_i32 m0, s36, 0xe000
	s_nop 0
	global_load_lds_dwordx4 v[148:149], off
	s_waitcnt vmcnt(8)
	s_waitcnt lgkmcnt(0)
	s_barrier
	s_waitcnt lgkmcnt(0)
	v_mfma_f32_16x16x32_bf16 v[144:147], v[116:119], v[194:197], 0
	v_mfma_f32_16x16x32_bf16 v[140:143], v[124:127], v[194:197], 0
	v_mfma_f32_16x16x32_bf16 v[112:115], v[116:119], v[202:205], 0
	v_mfma_f32_16x16x32_bf16 v[108:111], v[124:127], v[202:205], 0
	v_mfma_f32_16x16x32_bf16 v[96:99], v[116:119], v[210:213], 0
	v_mfma_f32_16x16x32_bf16 v[92:95], v[124:127], v[210:213], 0
	v_mfma_f32_16x16x32_bf16 v[80:83], v[116:119], v[218:221], 0
	v_mfma_f32_16x16x32_bf16 v[76:79], v[124:127], v[218:221], 0
	v_mfma_f32_16x16x32_bf16 v[144:147], v[120:123], v[198:201], v[144:147]
	v_mfma_f32_16x16x32_bf16 v[140:143], v[132:135], v[198:201], v[140:143]
	v_mfma_f32_16x16x32_bf16 v[112:115], v[120:123], v[206:209], v[112:115]
	v_mfma_f32_16x16x32_bf16 v[108:111], v[132:135], v[206:209], v[108:111]
	v_mfma_f32_16x16x32_bf16 v[96:99], v[120:123], v[214:217], v[96:99]
	v_mfma_f32_16x16x32_bf16 v[92:95], v[132:135], v[214:217], v[92:95]
	v_mfma_f32_16x16x32_bf16 v[80:83], v[120:123], v[222:225], v[80:83]
	v_mfma_f32_16x16x32_bf16 v[76:79], v[132:135], v[222:225], v[76:79]
	v_mfma_f32_16x16x32_bf16 v[136:139], v[178:181], v[194:197], 0
	v_mfma_f32_16x16x32_bf16 v[128:131], v[186:189], v[194:197], 0
	v_mfma_f32_16x16x32_bf16 v[104:107], v[178:181], v[202:205], 0
	v_mfma_f32_16x16x32_bf16 v[100:103], v[186:189], v[202:205], 0
	v_mfma_f32_16x16x32_bf16 v[88:91], v[178:181], v[210:213], 0
	v_mfma_f32_16x16x32_bf16 v[84:87], v[186:189], v[210:213], 0
	v_mfma_f32_16x16x32_bf16 v[72:75], v[178:181], v[218:221], 0
	v_mfma_f32_16x16x32_bf16 v[68:71], v[186:189], v[218:221], 0
	v_mfma_f32_16x16x32_bf16 v[136:139], v[182:185], v[198:201], v[136:139]
	v_mfma_f32_16x16x32_bf16 v[128:131], v[190:193], v[198:201], v[128:131]
	v_mfma_f32_16x16x32_bf16 v[104:107], v[182:185], v[206:209], v[104:107]
	v_mfma_f32_16x16x32_bf16 v[100:103], v[190:193], v[206:209], v[100:103]
	v_mfma_f32_16x16x32_bf16 v[88:91], v[182:185], v[214:217], v[88:91]
	v_mfma_f32_16x16x32_bf16 v[84:87], v[190:193], v[214:217], v[84:87]
	v_mfma_f32_16x16x32_bf16 v[72:75], v[182:185], v[222:225], v[72:75]
	v_mfma_f32_16x16x32_bf16 v[68:71], v[190:193], v[222:225], v[68:71]
	s_barrier
	s_add_i32 s50, s50, s26
	v_lshl_add_u64 v[148:149], s[20:21], 0, v[168:169]
	s_mov_b32 m0, s50
	ds_read_b128 v[194:197], v176 offset:16384
	ds_read_b128 v[198:201], v176 offset:17408
	ds_read_b128 v[202:205], v176 offset:18432
	ds_read_b128 v[206:209], v176 offset:19456
	ds_read_b128 v[210:213], v176 offset:20480
	ds_read_b128 v[214:217], v176 offset:21504
	ds_read_b128 v[218:221], v176 offset:22528
	ds_read_b128 v[222:225], v176 offset:23552
	global_load_lds_dwordx4 v[148:149], off
	s_add_i32 m0, s50, 0x2000
	s_add_u32 s50, s20, 0x40000
	v_lshl_add_u64 v[150:151], s[20:21], 0, v[0:1]
	s_addc_u32 s51, s21, 0
	s_add_i32 s52, s52, s26
	global_load_lds_dwordx4 v[150:151], off
	v_lshl_add_u64 v[226:227], s[50:51], 0, v[168:169]
	s_mov_b32 m0, s52
	v_lshl_add_u64 v[238:239], s[22:23], 0, v[166:167]
	global_load_lds_dwordx4 v[226:227], off
	v_lshl_add_u64 v[226:227], s[50:51], 0, v[0:1]
	s_add_i32 m0, s52, 0x2000
	s_nop 0
	global_load_lds_dwordx4 v[226:227], off
	v_lshl_add_u64 v[226:227], s[22:23], 0, v[170:171]
	s_mov_b32 m0, s36
	s_nop 0
	global_load_lds_dwordx4 v[226:227], off
	s_mov_b32 m0, s37
	s_nop 0
	global_load_lds_dwordx4 v[238:239], off
	s_waitcnt vmcnt(8)
	s_waitcnt lgkmcnt(0)
	s_barrier
; #define PG8_STAGE(bufoff, gbase, voff) do { _Pragma("unroll") for (int _i = 0; _i < 2; ++_i) \
;         __builtin_amdgcn_global_load_lds((const unsigned*)((const char*)(gbase) + (voff)[_i]), (PG8_LAS unsigned*)(lds + (bufoff) + ldsw + _i * 8192), 16, 0, 0); } while (0)
; #define PG8_LDA(dst, b, h) do { _Pragma("unroll") for (int m = 0; m < 4; ++m) _Pragma("unroll") for (int k = 0; k < 2; ++k) dst[m][k] = *(const PG8_LAS bf16x8*)(lds + PG8_SA(b, h) + aoff + m * 2048 + k * 1024); } while (0)
; #define PG8_LDB(dst, b, h) do { _Pragma("unroll") for (int n = 0; n < 2; ++n) _Pragma("unroll") for (int k = 0; k < 2; ++k) dst[n][k] = *(const PG8_LAS bf16x8*)(lds + PG8_SB(b, h) + boff + n * 2048 + k * 1024); } while (0)
; #define PG8_MMA(ai, bj, At, Bt) do { __builtin_amdgcn_s_setprio(1); _Pragma("unroll") for (int m = 0; m < 4; ++m) _Pragma("unroll") for (int n = 0; n < 2; ++n) _Pragma("unroll") for (int k = 0; k < 2; ++k) \
;         acc[ai][bj][m][n] = __builtin_amdgcn_mfma_f32_16x16x32_bf16(Bt[n][k], At[m][k], acc[ai][bj][m][n], 0, 0, 0); __builtin_amdgcn_s_setprio(0); } while (0)
; #define PG8_WAIT_V(n) asm volatile("s_waitcnt vmcnt(" #n ")" ::: "memory")
; #define PG8_WAIT_L(n) asm volatile("s_waitcnt lgkmcnt(" #n ")" ::: "memory")
; #define PG8_BAR __builtin_amdgcn_s_barrier()
; #define PG8_SCHED __builtin_amdgcn_sched_barrier(0)
; template <class Epi, class Sched, bool ALIGN_EPI = false, bool SP2 = false>
; __device__ __forceinline__ void gemm_phase(PG8_LAS unsigned char* lds, const Gemm g, const Sched& S, const Epi& E, const int tid) {
;     ...
;             PG8_WAIT_V(8); PG8_WAIT_L(0); PG8_BAR; PG8_MMA(1, 0, At, B0); PG8_MMA(1, 1, At, B1); PG8_BAR; PG8_SCHED;
;             PG8_LDB(B0, 1, 0); PG8_LDB(B1, 1, 1); PG8_SCHED; PG8_LDA(At, 1, 0); PG8_STAGE(PG8_SA(0, 1), a2 + hstep, voffA);
;             PG8_WAIT_V(8); PG8_WAIT_L(0); PG8_BAR; PG8_MMA(0, 0, At, B0); PG8_MMA(0, 1, At, B1); PG8_BAR; PG8_SCHED;
	s_waitcnt lgkmcnt(0)
	v_mfma_f32_16x16x32_bf16 v[64:67], v[116:119], v[194:197], 0
	v_mfma_f32_16x16x32_bf16 v[60:63], v[124:127], v[194:197], 0
	v_mfma_f32_16x16x32_bf16 v[56:59], v[116:119], v[202:205], 0
	v_mfma_f32_16x16x32_bf16 v[48:51], v[124:127], v[202:205], 0
	v_mfma_f32_16x16x32_bf16 v[40:43], v[116:119], v[210:213], 0
	v_mfma_f32_16x16x32_bf16 v[32:35], v[124:127], v[210:213], 0
	v_mfma_f32_16x16x32_bf16 v[24:27], v[116:119], v[218:221], 0
	v_mfma_f32_16x16x32_bf16 v[16:19], v[124:127], v[218:221], 0
	v_mfma_f32_16x16x32_bf16 v[64:67], v[120:123], v[198:201], v[64:67]
	v_mfma_f32_16x16x32_bf16 v[60:63], v[132:135], v[198:201], v[60:63]
	v_mfma_f32_16x16x32_bf16 v[56:59], v[120:123], v[206:209], v[56:59]
	v_mfma_f32_16x16x32_bf16 v[48:51], v[132:135], v[206:209], v[48:51]
	v_mfma_f32_16x16x32_bf16 v[40:43], v[120:123], v[214:217], v[40:43]
	v_mfma_f32_16x16x32_bf16 v[32:35], v[132:135], v[214:217], v[32:35]
	v_mfma_f32_16x16x32_bf16 v[24:27], v[120:123], v[222:225], v[24:27]
	v_mfma_f32_16x16x32_bf16 v[16:19], v[132:135], v[222:225], v[16:19]
	v_mfma_f32_16x16x32_bf16 v[52:55], v[178:181], v[194:197], 0
	v_mfma_f32_16x16x32_bf16 v[44:47], v[186:189], v[194:197], 0
	v_mfma_f32_16x16x32_bf16 v[36:39], v[178:181], v[202:205], 0
	v_mfma_f32_16x16x32_bf16 v[28:31], v[186:189], v[202:205], 0
	v_mfma_f32_16x16x32_bf16 v[20:23], v[178:181], v[210:213], 0
	v_mfma_f32_16x16x32_bf16 v[12:15], v[186:189], v[210:213], 0
	v_mfma_f32_16x16x32_bf16 v[8:11], v[178:181], v[218:221], 0
	v_mfma_f32_16x16x32_bf16 v[4:7], v[186:189], v[218:221], 0
	v_mfma_f32_16x16x32_bf16 v[52:55], v[182:185], v[198:201], v[52:55]
	v_mfma_f32_16x16x32_bf16 v[44:47], v[190:193], v[198:201], v[44:47]
	v_mfma_f32_16x16x32_bf16 v[36:39], v[182:185], v[206:209], v[36:39]
	v_mfma_f32_16x16x32_bf16 v[28:31], v[190:193], v[206:209], v[28:31]
	v_mfma_f32_16x16x32_bf16 v[20:23], v[182:185], v[214:217], v[20:23]
	v_mfma_f32_16x16x32_bf16 v[12:15], v[190:193], v[214:217], v[12:15]
	v_mfma_f32_16x16x32_bf16 v[8:11], v[182:185], v[222:225], v[8:11]
	v_mfma_f32_16x16x32_bf16 v[4:7], v[190:193], v[222:225], v[4:7]
	s_barrier
	s_add_i32 s50, 0, 0x18000
	s_add_i32 s51, 0, 0x1c000
	v_add_u32_e32 v132, s50, v153
	v_add_u32_e32 v177, s51, v153
	ds_read_b128 v[116:119], v132
	ds_read_b128 v[120:123], v132 offset:1024
	ds_read_b128 v[124:127], v132 offset:2048
	ds_read_b128 v[132:135], v132 offset:3072
	ds_read_b128 v[178:181], v177
	ds_read_b128 v[182:185], v177 offset:1024
	ds_read_b128 v[186:189], v177 offset:2048
	ds_read_b128 v[190:193], v177 offset:3072
	s_add_u32 s22, s22, 0x40000
	s_addc_u32 s23, s23, 0
	s_mov_b32 m0, s38
	v_lshl_add_u64 v[240:241], s[22:23], 0, v[170:171]
	ds_read_b128 v[194:197], v176 offset:32768
	ds_read_b128 v[198:201], v176 offset:33792
	ds_read_b128 v[202:205], v176 offset:34816
	ds_read_b128 v[206:209], v176 offset:35840
	ds_read_b128 v[210:213], v176 offset:36864
	ds_read_b128 v[214:217], v176 offset:37888
	ds_read_b128 v[218:221], v176 offset:38912
	ds_read_b128 v[222:225], v176 offset:39936
	global_load_lds_dwordx4 v[240:241], off
	v_lshl_add_u64 v[240:241], s[22:23], 0, v[166:167]
	s_mov_b32 m0, s39
	s_nop 0
	global_load_lds_dwordx4 v[240:241], off
	s_waitcnt vmcnt(8)
	s_waitcnt lgkmcnt(0)
	s_barrier
	s_waitcnt lgkmcnt(0)
	v_mfma_f32_16x16x32_bf16 v[144:147], v[116:119], v[194:197], v[144:147]
	v_mfma_f32_16x16x32_bf16 v[140:143], v[124:127], v[194:197], v[140:143]
	v_mfma_f32_16x16x32_bf16 v[112:115], v[116:119], v[202:205], v[112:115]
	v_mfma_f32_16x16x32_bf16 v[108:111], v[124:127], v[202:205], v[108:111]
	v_mfma_f32_16x16x32_bf16 v[96:99], v[116:119], v[210:213], v[96:99]
	v_mfma_f32_16x16x32_bf16 v[92:95], v[124:127], v[210:213], v[92:95]
	v_mfma_f32_16x16x32_bf16 v[80:83], v[116:119], v[218:221], v[80:83]
	v_mfma_f32_16x16x32_bf16 v[76:79], v[124:127], v[218:221], v[76:79]
	v_mfma_f32_16x16x32_bf16 v[144:147], v[120:123], v[198:201], v[144:147]
	v_mfma_f32_16x16x32_bf16 v[140:143], v[132:135], v[198:201], v[140:143]
	v_mfma_f32_16x16x32_bf16 v[112:115], v[120:123], v[206:209], v[112:115]
	v_mfma_f32_16x16x32_bf16 v[108:111], v[132:135], v[206:209], v[108:111]
	v_mfma_f32_16x16x32_bf16 v[96:99], v[120:123], v[214:217], v[96:99]
	v_mfma_f32_16x16x32_bf16 v[92:95], v[132:135], v[214:217], v[92:95]
	v_mfma_f32_16x16x32_bf16 v[80:83], v[120:123], v[222:225], v[80:83]
	v_mfma_f32_16x16x32_bf16 v[76:79], v[132:135], v[222:225], v[76:79]
	v_mfma_f32_16x16x32_bf16 v[136:139], v[178:181], v[194:197], v[136:139]
	v_mfma_f32_16x16x32_bf16 v[128:131], v[186:189], v[194:197], v[128:131]
	v_mfma_f32_16x16x32_bf16 v[104:107], v[178:181], v[202:205], v[104:107]
	v_mfma_f32_16x16x32_bf16 v[100:103], v[186:189], v[202:205], v[100:103]
	v_mfma_f32_16x16x32_bf16 v[88:91], v[178:181], v[210:213], v[88:91]
	v_mfma_f32_16x16x32_bf16 v[84:87], v[186:189], v[210:213], v[84:87]
	v_mfma_f32_16x16x32_bf16 v[72:75], v[178:181], v[218:221], v[72:75]
	v_mfma_f32_16x16x32_bf16 v[68:71], v[186:189], v[218:221], v[68:71]
	v_mfma_f32_16x16x32_bf16 v[136:139], v[182:185], v[198:201], v[136:139]
	v_mfma_f32_16x16x32_bf16 v[128:131], v[190:193], v[198:201], v[128:131]
	v_mfma_f32_16x16x32_bf16 v[104:107], v[182:185], v[206:209], v[104:107]
	v_mfma_f32_16x16x32_bf16 v[100:103], v[190:193], v[206:209], v[100:103]
	v_mfma_f32_16x16x32_bf16 v[88:91], v[182:185], v[214:217], v[88:91]
	v_mfma_f32_16x16x32_bf16 v[84:87], v[190:193], v[214:217], v[84:87]
	v_mfma_f32_16x16x32_bf16 v[72:75], v[182:185], v[222:225], v[72:75]
	v_mfma_f32_16x16x32_bf16 v[68:71], v[190:193], v[222:225], v[68:71]
	s_barrier
; #define PG8_STAGE(bufoff, gbase, voff) do { _Pragma("unroll") for (int _i = 0; _i < 2; ++_i) \
;         __builtin_amdgcn_global_load_lds((const unsigned*)((const char*)(gbase) + (voff)[_i]), (PG8_LAS unsigned*)(lds + (bufoff) + ldsw + _i * 8192), 16, 0, 0); } while (0)
; #define PG8_LDA(dst, b, h) do { _Pragma("unroll") for (int m = 0; m < 4; ++m) _Pragma("unroll") for (int k = 0; k < 2; ++k) dst[m][k] = *(const PG8_LAS bf16x8*)(lds + PG8_SA(b, h) + aoff + m * 2048 + k * 1024); } while (0)
; #define PG8_MMA(ai, bj, At, Bt) do { __builtin_amdgcn_s_setprio(1); _Pragma("unroll") for (int m = 0; m < 4; ++m) _Pragma("unroll") for (int n = 0; n < 2; ++n) _Pragma("unroll") for (int k = 0; k < 2; ++k) \
;         acc[ai][bj][m][n] = __builtin_amdgcn_mfma_f32_16x16x32_bf16(Bt[n][k], At[m][k], acc[ai][bj][m][n], 0, 0, 0); __builtin_amdgcn_s_setprio(0); } while (0)
; #define PG8_WAIT_V(n) asm volatile("s_waitcnt vmcnt(" #n ")" ::: "memory")
; #define PG8_WAIT_L(n) asm volatile("s_waitcnt lgkmcnt(" #n ")" ::: "memory")
; #define PG8_BAR __builtin_amdgcn_s_barrier()
; #define PG8_SCHED __builtin_amdgcn_sched_barrier(0)
; template <class Epi, class Sched, bool ALIGN_EPI = false, bool SP2 = false>
; __device__ __forceinline__ void gemm_phase(PG8_LAS unsigned char* lds, const Gemm g, const Sched& S, const Epi& E, const int tid) {
;     ...
;             PG8_LDA(At, 1, 1); PG8_STAGE(PG8_SB(1, 0), b3, voffB); PG8_STAGE(PG8_SB(1, 1), b3 + hstep, voffB); PG8_STAGE(PG8_SA(1, 0), a3, voffA);
;             PG8_WAIT_V(8); PG8_WAIT_L(0); PG8_BAR; PG8_MMA(1, 0, At, B0); PG8_MMA(1, 1, At, B1); PG8_BAR; PG8_SCHED;
	s_add_i32 s22, s50, s26
	v_lshl_add_u64 v[148:149], v[148:149], 0, s[0:1]
	s_mov_b32 m0, s22
	ds_read_b128 v[194:197], v176 offset:49152
	ds_read_b128 v[198:201], v176 offset:50176
	ds_read_b128 v[202:205], v176 offset:51200
	ds_read_b128 v[206:209], v176 offset:52224
	ds_read_b128 v[210:213], v176 offset:53248
	ds_read_b128 v[214:217], v176 offset:54272
	ds_read_b128 v[218:221], v176 offset:55296
	ds_read_b128 v[222:225], v176 offset:56320
	global_load_lds_dwordx4 v[148:149], off
	s_add_i32 m0, s22, 0x2000
	s_add_u32 s20, s20, 0x40080
	v_lshl_add_u64 v[148:149], v[150:151], 0, s[0:1]
	s_addc_u32 s21, s21, 0
	s_add_i32 s22, s51, s26
	global_load_lds_dwordx4 v[148:149], off
	v_lshl_add_u64 v[148:149], s[20:21], 0, v[168:169]
	s_mov_b32 m0, s22
	s_nop 0
	global_load_lds_dwordx4 v[148:149], off
	v_lshl_add_u64 v[148:149], s[20:21], 0, v[0:1]
	s_add_i32 m0, s22, 0x2000
	s_nop 0
	global_load_lds_dwordx4 v[148:149], off
	v_lshl_add_u64 v[148:149], v[226:227], 0, s[0:1]
	s_mov_b32 m0, s40
	s_nop 0
	global_load_lds_dwordx4 v[148:149], off
	v_lshl_add_u64 v[148:149], v[238:239], 0, s[0:1]
	s_mov_b32 m0, s41
	s_nop 0
	global_load_lds_dwordx4 v[148:149], off
	s_waitcnt vmcnt(8)
	s_waitcnt lgkmcnt(0)
	s_barrier
	s_waitcnt lgkmcnt(0)
	v_mfma_f32_16x16x32_bf16 v[64:67], v[116:119], v[194:197], v[64:67]
	v_mfma_f32_16x16x32_bf16 v[60:63], v[124:127], v[194:197], v[60:63]
	v_mfma_f32_16x16x32_bf16 v[56:59], v[116:119], v[202:205], v[56:59]
	v_mfma_f32_16x16x32_bf16 v[48:51], v[124:127], v[202:205], v[48:51]
	v_mfma_f32_16x16x32_bf16 v[40:43], v[116:119], v[210:213], v[40:43]
	v_mfma_f32_16x16x32_bf16 v[32:35], v[124:127], v[210:213], v[32:35]
	v_mfma_f32_16x16x32_bf16 v[24:27], v[116:119], v[218:221], v[24:27]
	v_mfma_f32_16x16x32_bf16 v[16:19], v[124:127], v[218:221], v[16:19]
	v_mfma_f32_16x16x32_bf16 v[64:67], v[120:123], v[198:201], v[64:67]
	v_mfma_f32_16x16x32_bf16 v[60:63], v[132:135], v[198:201], v[60:63]
	v_mfma_f32_16x16x32_bf16 v[56:59], v[120:123], v[206:209], v[56:59]
	v_mfma_f32_16x16x32_bf16 v[48:51], v[132:135], v[206:209], v[48:51]
	v_mfma_f32_16x16x32_bf16 v[40:43], v[120:123], v[214:217], v[40:43]
	v_mfma_f32_16x16x32_bf16 v[32:35], v[132:135], v[214:217], v[32:35]
	v_mfma_f32_16x16x32_bf16 v[24:27], v[120:123], v[222:225], v[24:27]
	v_mfma_f32_16x16x32_bf16 v[16:19], v[132:135], v[222:225], v[16:19]
	v_mfma_f32_16x16x32_bf16 v[52:55], v[178:181], v[194:197], v[52:55]
	v_mfma_f32_16x16x32_bf16 v[44:47], v[186:189], v[194:197], v[44:47]
	v_mfma_f32_16x16x32_bf16 v[36:39], v[178:181], v[202:205], v[36:39]
	v_mfma_f32_16x16x32_bf16 v[28:31], v[186:189], v[202:205], v[28:31]
	v_mfma_f32_16x16x32_bf16 v[20:23], v[178:181], v[210:213], v[20:23]
	v_mfma_f32_16x16x32_bf16 v[12:15], v[186:189], v[210:213], v[12:15]
	v_mfma_f32_16x16x32_bf16 v[8:11], v[178:181], v[218:221], v[8:11]
	v_mfma_f32_16x16x32_bf16 v[4:7], v[186:189], v[218:221], v[4:7]
	v_mfma_f32_16x16x32_bf16 v[52:55], v[182:185], v[198:201], v[52:55]
	v_mfma_f32_16x16x32_bf16 v[44:47], v[190:193], v[198:201], v[44:47]
	v_mfma_f32_16x16x32_bf16 v[36:39], v[182:185], v[206:209], v[36:39]
	v_mfma_f32_16x16x32_bf16 v[28:31], v[190:193], v[206:209], v[28:31]
	v_mfma_f32_16x16x32_bf16 v[20:23], v[182:185], v[214:217], v[20:23]
	v_mfma_f32_16x16x32_bf16 v[12:15], v[190:193], v[214:217], v[12:15]
	v_mfma_f32_16x16x32_bf16 v[8:11], v[182:185], v[222:225], v[8:11]
	v_mfma_f32_16x16x32_bf16 v[4:7], v[190:193], v[222:225], v[4:7]
	s_barrier
	s_add_i32 s49, s49, 2
	s_add_u32 s18, s18, 0x100
	s_addc_u32 s19, s19, 0
	s_add_u32 s47, s47, 0x100
	s_addc_u32 s48, s48, 0
	s_cmp_gt_u32 s49, 13
	s_cbranch_scc0 .LBB0_99
	s_branch .Lpeel_exit0
	.p2align	6

; #define PG8_STAGE(bufoff, gbase, voff) do { _Pragma("unroll") for (int _i = 0; _i < 2; ++_i) \
;         __builtin_amdgcn_global_load_lds((const unsigned*)((const char*)(gbase) + (voff)[_i]), (PG8_LAS unsigned*)(lds + (bufoff) + ldsw + _i * 8192), 16, 0, 0); } while (0)
; #define PG8_LDA(dst, b, h) do { _Pragma("unroll") for (int m = 0; m < 4; ++m) _Pragma("unroll") for (int k = 0; k < 2; ++k) dst[m][k] = *(const PG8_LAS bf16x8*)(lds + PG8_SA(b, h) + aoff + m * 2048 + k * 1024); } while (0)
; #define PG8_LDB(dst, b, h) do { _Pragma("unroll") for (int n = 0; n < 2; ++n) _Pragma("unroll") for (int k = 0; k < 2; ++k) dst[n][k] = *(const PG8_LAS bf16x8*)(lds + PG8_SB(b, h) + boff + n * 2048 + k * 1024); } while (0)
; #define PG8_MMA(ai, bj, At, Bt) do { __builtin_amdgcn_s_setprio(1); _Pragma("unroll") for (int m = 0; m < 4; ++m) _Pragma("unroll") for (int n = 0; n < 2; ++n) _Pragma("unroll") for (int k = 0; k < 2; ++k) \
;         acc[ai][bj][m][n] = __builtin_amdgcn_mfma_f32_16x16x32_bf16(Bt[n][k], At[m][k], acc[ai][bj][m][n], 0, 0, 0); __builtin_amdgcn_s_setprio(0); } while (0)
; template <class Epi, class Sched, bool ALIGN_EPI = false, bool SP2 = false>
; __device__ __forceinline__ void gemm_phase(PG8_LAS unsigned char* lds, const Gemm g, const Sched& S, const Epi& E, const int tid) {
;     ...
;     for (;;) {
;         const bool has_next = S.next(ui + 1, nxt);
;         const char* nA = has_next ? (const char*)g.A + (size_t)nxt.pm * tstep : cA; const char* nB = has_next ? (const char*)g.Bt + (size_t)nxt.pn * tstep : cB;
;         for (int t = 0; t < nt; t += 2) {
;             const bool last = (t == nt - 2);
;             const char* a1 = cA + (size_t)(t + 1) * kstep;
;             const char* a2 = last ? nA : cA + (size_t)(t + 2) * kstep; const char* b2 = last ? nB : cB + (size_t)(t + 2) * kstep;
;             const char* a3 = a2 + kstep; const char* b3 = b2 + kstep;
;             if (last && has_next) S.a_ready(nxt);
;             if constexpr (SP2) {
;             PG8_LDB(B0, 0, 0); PG8_LDB(B1, 0, 1); PG8_SCHED; PG8_LDA(At, 0, 0); PG8_STAGE(PG8_SA(1, 1), a1 + hstep, voffA);
;             PG8_WAIT_V(8); PG8_WAIT_L(0); PG8_BAR; PG8_MMA(0, 0, At, B0); PG8_MMA(0, 1, At, B1); PG8_BAR; PG8_SCHED;
;             PG8_LDA(At, 0, 1); PG8_STAGE(PG8_SB(0, 0), b2, voffB); PG8_STAGE(PG8_SB(0, 1), b2 + hstep, voffB); PG8_STAGE(PG8_SA(0, 0), a2, voffA);
.LBB0_292:
	s_ashr_i32 s17, s16, 31
	s_lshl_b64 s[18:19], s[16:17], 19
	s_add_u32 s18, s34, s18
	s_addc_u32 s19, s40, s19
	s_and_b64 s[20:21], s[4:5], exec
	s_cselect_b32 s17, s19, s3
	s_cselect_b32 s23, s18, s2
	s_ashr_i32 s15, s14, 31
	s_lshl_b64 s[20:21], s[14:15], 19
	s_add_u32 s20, s41, s20
	s_addc_u32 s21, s42, s21
	s_and_b64 s[36:37], s[4:5], exec
	s_cselect_b32 s15, s21, s27
	s_cselect_b32 s51, s20, s26
	s_add_u32 s2, s2, 0x40080
	s_addc_u32 s3, s3, 0
	s_add_u32 s52, s26, 0x100
	v_mov_b32_e32 v12, 0
	s_addc_u32 s53, s27, 0
	s_mov_b32 s54, -2
	s_add_u32 s26, s2, 0xfffc0080
	s_addc_u32 s27, s3, -1
	s_add_i32 s55, 0, 0x10000
	s_cmp_eq_u32 s54, 12
	s_cselect_b32 s37, s17, s27
	s_cselect_b32 s36, s23, s26
	v_add_u32_e32 v146, s55, v165
	s_cselect_b32 s27, s15, s53
	s_cselect_b32 s26, s51, s52
	s_add_i32 s58, 0, 0x14000
	ds_read_b128 v[166:169], v146
	ds_read_b128 v[172:175], v146 offset:1024
	ds_read_b128 v[176:179], v146 offset:2048
	ds_read_b128 v[180:183], v146 offset:3072
	v_add_u32_e32 v146, s58, v165
	ds_read_b128 v[184:187], v146
	ds_read_b128 v[188:191], v146 offset:1024
	ds_read_b128 v[192:195], v146 offset:2048
	ds_read_b128 v[196:199], v146 offset:3072
	v_lshl_add_u64 v[146:147], s[2:3], 0, v[142:143]
	s_add_i32 m0, s25, 0xc000
	ds_read_b128 v[200:203], v171
	ds_read_b128 v[204:207], v171 offset:1024
	ds_read_b128 v[208:211], v171 offset:2048
	ds_read_b128 v[212:215], v171 offset:3072
	ds_read_b128 v[216:219], v171 offset:4096
	ds_read_b128 v[220:223], v171 offset:5120
	ds_read_b128 v[224:227], v171 offset:6144
	ds_read_b128 v[238:241], v171 offset:7168
	global_load_lds_dwordx4 v[146:147], off
	v_lshl_add_u64 v[146:147], s[2:3], 0, v[144:145]
	s_add_i32 m0, s25, 0xe000
	s_nop 0
	global_load_lds_dwordx4 v[146:147], off
	s_waitcnt vmcnt(8)
	s_waitcnt lgkmcnt(0)
	s_barrier
	s_waitcnt lgkmcnt(0)
	v_mfma_f32_16x16x32_bf16 v[72:75], v[166:169], v[200:203], 0
	v_mfma_f32_16x16x32_bf16 v[68:71], v[176:179], v[200:203], 0
	v_mfma_f32_16x16x32_bf16 v[64:67], v[166:169], v[208:211], 0
	v_mfma_f32_16x16x32_bf16 v[60:63], v[176:179], v[208:211], 0
	v_mfma_f32_16x16x32_bf16 v[56:59], v[166:169], v[216:219], 0
	v_mfma_f32_16x16x32_bf16 v[52:55], v[176:179], v[216:219], 0
	v_mfma_f32_16x16x32_bf16 v[48:51], v[166:169], v[224:227], 0
	v_mfma_f32_16x16x32_bf16 v[44:47], v[176:179], v[224:227], 0
	v_mfma_f32_16x16x32_bf16 v[72:75], v[172:175], v[204:207], v[72:75]
	v_mfma_f32_16x16x32_bf16 v[68:71], v[180:183], v[204:207], v[68:71]
	v_mfma_f32_16x16x32_bf16 v[64:67], v[172:175], v[212:215], v[64:67]
	v_mfma_f32_16x16x32_bf16 v[60:63], v[180:183], v[212:215], v[60:63]
	v_mfma_f32_16x16x32_bf16 v[56:59], v[172:175], v[220:223], v[56:59]
	v_mfma_f32_16x16x32_bf16 v[52:55], v[180:183], v[220:223], v[52:55]
	v_mfma_f32_16x16x32_bf16 v[48:51], v[172:175], v[238:241], v[48:51]
	v_mfma_f32_16x16x32_bf16 v[44:47], v[180:183], v[238:241], v[44:47]
	v_mfma_f32_16x16x32_bf16 v[128:131], v[184:187], v[200:203], 0
	v_mfma_f32_16x16x32_bf16 v[124:127], v[192:195], v[200:203], 0
	v_mfma_f32_16x16x32_bf16 v[120:123], v[184:187], v[208:211], 0
	v_mfma_f32_16x16x32_bf16 v[116:119], v[192:195], v[208:211], 0
	v_mfma_f32_16x16x32_bf16 v[112:115], v[184:187], v[216:219], 0
	v_mfma_f32_16x16x32_bf16 v[108:111], v[192:195], v[216:219], 0
	v_mfma_f32_16x16x32_bf16 v[104:107], v[184:187], v[224:227], 0
	v_mfma_f32_16x16x32_bf16 v[100:103], v[192:195], v[224:227], 0
	v_mfma_f32_16x16x32_bf16 v[128:131], v[188:191], v[204:207], v[128:131]
	v_mfma_f32_16x16x32_bf16 v[124:127], v[196:199], v[204:207], v[124:127]
	v_mfma_f32_16x16x32_bf16 v[120:123], v[188:191], v[212:215], v[120:123]
	v_mfma_f32_16x16x32_bf16 v[116:119], v[196:199], v[212:215], v[116:119]
	v_mfma_f32_16x16x32_bf16 v[112:115], v[188:191], v[220:223], v[112:115]
	v_mfma_f32_16x16x32_bf16 v[108:111], v[196:199], v[220:223], v[108:111]
	v_mfma_f32_16x16x32_bf16 v[104:107], v[188:191], v[238:241], v[104:107]
	v_mfma_f32_16x16x32_bf16 v[100:103], v[196:199], v[238:241], v[100:103]
	s_barrier
	s_add_i32 s55, s55, s43
	v_lshl_add_u64 v[146:147], s[26:27], 0, v[132:133]
	s_mov_b32 m0, s55
	ds_read_b128 v[200:203], v171 offset:16384
	ds_read_b128 v[204:207], v171 offset:17408
	ds_read_b128 v[208:211], v171 offset:18432
	ds_read_b128 v[212:215], v171 offset:19456
	ds_read_b128 v[216:219], v171 offset:20480
	ds_read_b128 v[220:223], v171 offset:21504
	ds_read_b128 v[224:227], v171 offset:22528
	ds_read_b128 v[238:241], v171 offset:23552
	global_load_lds_dwordx4 v[146:147], off
	s_add_i32 m0, s55, 0x2000
	s_add_u32 s56, s26, 0x40000
	v_lshl_add_u64 v[148:149], s[26:27], 0, v[136:137]
	s_addc_u32 s57, s27, 0
	s_add_i32 s55, s58, s43
	global_load_lds_dwordx4 v[148:149], off
	v_lshl_add_u64 v[150:151], s[56:57], 0, v[132:133]
	s_mov_b32 m0, s55
	v_lshl_add_u64 v[242:243], s[36:37], 0, v[134:135]
	global_load_lds_dwordx4 v[150:151], off
	v_lshl_add_u64 v[150:151], s[56:57], 0, v[136:137]
	s_add_i32 m0, s55, 0x2000
	s_nop 0
	global_load_lds_dwordx4 v[150:151], off
	v_lshl_add_u64 v[150:151], s[36:37], 0, v[0:1]
	s_mov_b32 m0, s25
	s_nop 0
	global_load_lds_dwordx4 v[150:151], off
	s_mov_b32 m0, s44
	s_nop 0
	global_load_lds_dwordx4 v[242:243], off
	s_waitcnt vmcnt(8)
	s_waitcnt lgkmcnt(0)
	s_barrier
; #define PG8_STAGE(bufoff, gbase, voff) do { _Pragma("unroll") for (int _i = 0; _i < 2; ++_i) \
;         __builtin_amdgcn_global_load_lds((const unsigned*)((const char*)(gbase) + (voff)[_i]), (PG8_LAS unsigned*)(lds + (bufoff) + ldsw + _i * 8192), 16, 0, 0); } while (0)
; #define PG8_LDA(dst, b, h) do { _Pragma("unroll") for (int m = 0; m < 4; ++m) _Pragma("unroll") for (int k = 0; k < 2; ++k) dst[m][k] = *(const PG8_LAS bf16x8*)(lds + PG8_SA(b, h) + aoff + m * 2048 + k * 1024); } while (0)
; #define PG8_LDB(dst, b, h) do { _Pragma("unroll") for (int n = 0; n < 2; ++n) _Pragma("unroll") for (int k = 0; k < 2; ++k) dst[n][k] = *(const PG8_LAS bf16x8*)(lds + PG8_SB(b, h) + boff + n * 2048 + k * 1024); } while (0)
; #define PG8_MMA(ai, bj, At, Bt) do { __builtin_amdgcn_s_setprio(1); _Pragma("unroll") for (int m = 0; m < 4; ++m) _Pragma("unroll") for (int n = 0; n < 2; ++n) _Pragma("unroll") for (int k = 0; k < 2; ++k) \
;         acc[ai][bj][m][n] = __builtin_amdgcn_mfma_f32_16x16x32_bf16(Bt[n][k], At[m][k], acc[ai][bj][m][n], 0, 0, 0); __builtin_amdgcn_s_setprio(0); } while (0)
; #define PG8_WAIT_V(n) asm volatile("s_waitcnt vmcnt(" #n ")" ::: "memory")
; #define PG8_WAIT_L(n) asm volatile("s_waitcnt lgkmcnt(" #n ")" ::: "memory")
; #define PG8_BAR __builtin_amdgcn_s_barrier()
; #define PG8_SCHED __builtin_amdgcn_sched_barrier(0)
; template <class Epi, class Sched, bool ALIGN_EPI = false, bool SP2 = false>
; __device__ __forceinline__ void gemm_phase(PG8_LAS unsigned char* lds, const Gemm g, const Sched& S, const Epi& E, const int tid) {
;     ...
;             PG8_WAIT_V(8); PG8_WAIT_L(0); PG8_BAR; PG8_MMA(1, 0, At, B0); PG8_MMA(1, 1, At, B1); PG8_BAR; PG8_SCHED;
;             PG8_LDB(B0, 1, 0); PG8_LDB(B1, 1, 1); PG8_SCHED; PG8_LDA(At, 1, 0); PG8_STAGE(PG8_SA(0, 1), a2 + hstep, voffA);
;             PG8_WAIT_V(8); PG8_WAIT_L(0); PG8_BAR; PG8_MMA(0, 0, At, B0); PG8_MMA(0, 1, At, B1); PG8_BAR; PG8_SCHED;
	s_waitcnt lgkmcnt(0)
	v_mfma_f32_16x16x32_bf16 v[40:43], v[166:169], v[200:203], 0
	v_mfma_f32_16x16x32_bf16 v[36:39], v[176:179], v[200:203], 0
	v_mfma_f32_16x16x32_bf16 v[32:35], v[166:169], v[208:211], 0
	v_mfma_f32_16x16x32_bf16 v[28:31], v[176:179], v[208:211], 0
	v_mfma_f32_16x16x32_bf16 v[24:27], v[166:169], v[216:219], 0
	v_mfma_f32_16x16x32_bf16 v[20:23], v[176:179], v[216:219], 0
	v_mfma_f32_16x16x32_bf16 v[8:11], v[166:169], v[224:227], 0
	v_mfma_f32_16x16x32_bf16 v[4:7], v[176:179], v[224:227], 0
	v_mfma_f32_16x16x32_bf16 v[40:43], v[172:175], v[204:207], v[40:43]
	v_mfma_f32_16x16x32_bf16 v[36:39], v[180:183], v[204:207], v[36:39]
	v_mfma_f32_16x16x32_bf16 v[32:35], v[172:175], v[212:215], v[32:35]
	v_mfma_f32_16x16x32_bf16 v[28:31], v[180:183], v[212:215], v[28:31]
	v_mfma_f32_16x16x32_bf16 v[24:27], v[172:175], v[220:223], v[24:27]
	v_mfma_f32_16x16x32_bf16 v[20:23], v[180:183], v[220:223], v[20:23]
	v_mfma_f32_16x16x32_bf16 v[8:11], v[172:175], v[238:241], v[8:11]
	v_mfma_f32_16x16x32_bf16 v[4:7], v[180:183], v[238:241], v[4:7]
	v_mfma_f32_16x16x32_bf16 v[96:99], v[184:187], v[200:203], 0
	v_mfma_f32_16x16x32_bf16 v[92:95], v[192:195], v[200:203], 0
	v_mfma_f32_16x16x32_bf16 v[88:91], v[184:187], v[208:211], 0
	v_mfma_f32_16x16x32_bf16 v[84:87], v[192:195], v[208:211], 0
	v_mfma_f32_16x16x32_bf16 v[80:83], v[184:187], v[216:219], 0
	v_mfma_f32_16x16x32_bf16 v[76:79], v[192:195], v[216:219], 0
	v_mfma_f32_16x16x32_bf16 v[16:19], v[184:187], v[224:227], 0
	v_mfma_f32_16x16x32_bf16 v[12:15], v[192:195], v[224:227], 0
	v_mfma_f32_16x16x32_bf16 v[96:99], v[188:191], v[204:207], v[96:99]
	v_mfma_f32_16x16x32_bf16 v[92:95], v[196:199], v[204:207], v[92:95]
	v_mfma_f32_16x16x32_bf16 v[88:91], v[188:191], v[212:215], v[88:91]
	v_mfma_f32_16x16x32_bf16 v[84:87], v[196:199], v[212:215], v[84:87]
	v_mfma_f32_16x16x32_bf16 v[80:83], v[188:191], v[220:223], v[80:83]
	v_mfma_f32_16x16x32_bf16 v[76:79], v[196:199], v[220:223], v[76:79]
	v_mfma_f32_16x16x32_bf16 v[16:19], v[188:191], v[238:241], v[16:19]
	v_mfma_f32_16x16x32_bf16 v[12:15], v[196:199], v[238:241], v[12:15]
	s_barrier
	s_add_i32 s55, 0, 0x18000
	v_add_u32_e32 v153, s55, v165
	s_add_i32 s56, 0, 0x1c000
	ds_read_b128 v[166:169], v153
	ds_read_b128 v[172:175], v153 offset:1024
	ds_read_b128 v[176:179], v153 offset:2048
	ds_read_b128 v[180:183], v153 offset:3072
	v_add_u32_e32 v153, s56, v165
	ds_read_b128 v[184:187], v153
	ds_read_b128 v[188:191], v153 offset:1024
	ds_read_b128 v[192:195], v153 offset:2048
	ds_read_b128 v[196:199], v153 offset:3072
	s_add_u32 s36, s36, 0x40000
	s_addc_u32 s37, s37, 0
	s_mov_b32 m0, s45
	v_lshl_add_u64 v[244:245], s[36:37], 0, v[0:1]
	ds_read_b128 v[200:203], v171 offset:32768
	ds_read_b128 v[204:207], v171 offset:33792
	ds_read_b128 v[208:211], v171 offset:34816
	ds_read_b128 v[212:215], v171 offset:35840
	ds_read_b128 v[216:219], v171 offset:36864
	ds_read_b128 v[220:223], v171 offset:37888
	ds_read_b128 v[224:227], v171 offset:38912
	ds_read_b128 v[238:241], v171 offset:39936
	global_load_lds_dwordx4 v[244:245], off
	v_lshl_add_u64 v[244:245], s[36:37], 0, v[134:135]
	s_mov_b32 m0, s46
	s_nop 0
	global_load_lds_dwordx4 v[244:245], off
	s_waitcnt vmcnt(8)
	s_waitcnt lgkmcnt(0)
	s_barrier
	s_waitcnt lgkmcnt(0)
	v_mfma_f32_16x16x32_bf16 v[72:75], v[166:169], v[200:203], v[72:75]
	v_mfma_f32_16x16x32_bf16 v[68:71], v[176:179], v[200:203], v[68:71]
	v_mfma_f32_16x16x32_bf16 v[64:67], v[166:169], v[208:211], v[64:67]
	v_mfma_f32_16x16x32_bf16 v[60:63], v[176:179], v[208:211], v[60:63]
	v_mfma_f32_16x16x32_bf16 v[56:59], v[166:169], v[216:219], v[56:59]
	v_mfma_f32_16x16x32_bf16 v[52:55], v[176:179], v[216:219], v[52:55]
	v_mfma_f32_16x16x32_bf16 v[48:51], v[166:169], v[224:227], v[48:51]
	v_mfma_f32_16x16x32_bf16 v[44:47], v[176:179], v[224:227], v[44:47]
	v_mfma_f32_16x16x32_bf16 v[72:75], v[172:175], v[204:207], v[72:75]
	v_mfma_f32_16x16x32_bf16 v[68:71], v[180:183], v[204:207], v[68:71]
	v_mfma_f32_16x16x32_bf16 v[64:67], v[172:175], v[212:215], v[64:67]
	v_mfma_f32_16x16x32_bf16 v[60:63], v[180:183], v[212:215], v[60:63]
	v_mfma_f32_16x16x32_bf16 v[56:59], v[172:175], v[220:223], v[56:59]
	v_mfma_f32_16x16x32_bf16 v[52:55], v[180:183], v[220:223], v[52:55]
	v_mfma_f32_16x16x32_bf16 v[48:51], v[172:175], v[238:241], v[48:51]
	v_mfma_f32_16x16x32_bf16 v[44:47], v[180:183], v[238:241], v[44:47]
	v_mfma_f32_16x16x32_bf16 v[128:131], v[184:187], v[200:203], v[128:131]
	v_mfma_f32_16x16x32_bf16 v[124:127], v[192:195], v[200:203], v[124:127]
	v_mfma_f32_16x16x32_bf16 v[120:123], v[184:187], v[208:211], v[120:123]
	v_mfma_f32_16x16x32_bf16 v[116:119], v[192:195], v[208:211], v[116:119]
	v_mfma_f32_16x16x32_bf16 v[112:115], v[184:187], v[216:219], v[112:115]
	v_mfma_f32_16x16x32_bf16 v[108:111], v[192:195], v[216:219], v[108:111]
	v_mfma_f32_16x16x32_bf16 v[104:107], v[184:187], v[224:227], v[104:107]
	v_mfma_f32_16x16x32_bf16 v[100:103], v[192:195], v[224:227], v[100:103]
	v_mfma_f32_16x16x32_bf16 v[128:131], v[188:191], v[204:207], v[128:131]
	v_mfma_f32_16x16x32_bf16 v[124:127], v[196:199], v[204:207], v[124:127]
	v_mfma_f32_16x16x32_bf16 v[120:123], v[188:191], v[212:215], v[120:123]
	v_mfma_f32_16x16x32_bf16 v[116:119], v[196:199], v[212:215], v[116:119]
	v_mfma_f32_16x16x32_bf16 v[112:115], v[188:191], v[220:223], v[112:115]
	v_mfma_f32_16x16x32_bf16 v[108:111], v[196:199], v[220:223], v[108:111]
	v_mfma_f32_16x16x32_bf16 v[104:107], v[188:191], v[238:241], v[104:107]
	v_mfma_f32_16x16x32_bf16 v[100:103], v[196:199], v[238:241], v[100:103]
	s_barrier
; #define PG8_STAGE(bufoff, gbase, voff) do { _Pragma("unroll") for (int _i = 0; _i < 2; ++_i) \
;         __builtin_amdgcn_global_load_lds((const unsigned*)((const char*)(gbase) + (voff)[_i]), (PG8_LAS unsigned*)(lds + (bufoff) + ldsw + _i * 8192), 16, 0, 0); } while (0)
; #define PG8_LDA(dst, b, h) do { _Pragma("unroll") for (int m = 0; m < 4; ++m) _Pragma("unroll") for (int k = 0; k < 2; ++k) dst[m][k] = *(const PG8_LAS bf16x8*)(lds + PG8_SA(b, h) + aoff + m * 2048 + k * 1024); } while (0)
; #define PG8_MMA(ai, bj, At, Bt) do { __builtin_amdgcn_s_setprio(1); _Pragma("unroll") for (int m = 0; m < 4; ++m) _Pragma("unroll") for (int n = 0; n < 2; ++n) _Pragma("unroll") for (int k = 0; k < 2; ++k) \
;         acc[ai][bj][m][n] = __builtin_amdgcn_mfma_f32_16x16x32_bf16(Bt[n][k], At[m][k], acc[ai][bj][m][n], 0, 0, 0); __builtin_amdgcn_s_setprio(0); } while (0)
; #define PG8_WAIT_V(n) asm volatile("s_waitcnt vmcnt(" #n ")" ::: "memory")
; #define PG8_WAIT_L(n) asm volatile("s_waitcnt lgkmcnt(" #n ")" ::: "memory")
; #define PG8_BAR __builtin_amdgcn_s_barrier()
; #define PG8_SCHED __builtin_amdgcn_sched_barrier(0)
; template <class Epi, class Sched, bool ALIGN_EPI = false, bool SP2 = false>
; __device__ __forceinline__ void gemm_phase(PG8_LAS unsigned char* lds, const Gemm g, const Sched& S, const Epi& E, const int tid) {
;     ...
;             PG8_LDA(At, 1, 1); PG8_STAGE(PG8_SB(1, 0), b3, voffB); PG8_STAGE(PG8_SB(1, 1), b3 + hstep, voffB); PG8_STAGE(PG8_SA(1, 0), a3, voffA);
;             PG8_WAIT_V(8); PG8_WAIT_L(0); PG8_BAR; PG8_MMA(1, 0, At, B0); PG8_MMA(1, 1, At, B1); PG8_BAR; PG8_SCHED;
	s_add_i32 s36, s55, s43
	v_lshl_add_u64 v[146:147], v[146:147], 0, s[0:1]
	s_mov_b32 m0, s36
	ds_read_b128 v[200:203], v171 offset:49152
	ds_read_b128 v[204:207], v171 offset:50176
	ds_read_b128 v[208:211], v171 offset:51200
	ds_read_b128 v[212:215], v171 offset:52224
	ds_read_b128 v[216:219], v171 offset:53248
	ds_read_b128 v[220:223], v171 offset:54272
	ds_read_b128 v[224:227], v171 offset:55296
	ds_read_b128 v[238:241], v171 offset:56320
	global_load_lds_dwordx4 v[146:147], off
	s_add_i32 m0, s36, 0x2000
	s_add_u32 s26, s26, 0x40080
	v_lshl_add_u64 v[146:147], v[148:149], 0, s[0:1]
	s_addc_u32 s27, s27, 0
	s_add_i32 s36, s56, s43
	global_load_lds_dwordx4 v[146:147], off
	v_lshl_add_u64 v[146:147], s[26:27], 0, v[132:133]
	s_mov_b32 m0, s36
	s_nop 0
	global_load_lds_dwordx4 v[146:147], off
	v_lshl_add_u64 v[146:147], s[26:27], 0, v[136:137]
	s_add_i32 m0, s36, 0x2000
	s_nop 0
	global_load_lds_dwordx4 v[146:147], off
	v_lshl_add_u64 v[146:147], v[150:151], 0, s[0:1]
	s_mov_b32 m0, s48
	s_nop 0
	global_load_lds_dwordx4 v[146:147], off
	v_lshl_add_u64 v[146:147], v[242:243], 0, s[0:1]
	s_mov_b32 m0, s49
	s_nop 0
	global_load_lds_dwordx4 v[146:147], off
	s_waitcnt vmcnt(8)
	s_waitcnt lgkmcnt(0)
	s_barrier
	s_waitcnt lgkmcnt(0)
	v_mfma_f32_16x16x32_bf16 v[40:43], v[166:169], v[200:203], v[40:43]
	v_mfma_f32_16x16x32_bf16 v[36:39], v[176:179], v[200:203], v[36:39]
	v_mfma_f32_16x16x32_bf16 v[32:35], v[166:169], v[208:211], v[32:35]
	v_mfma_f32_16x16x32_bf16 v[28:31], v[176:179], v[208:211], v[28:31]
	v_mfma_f32_16x16x32_bf16 v[24:27], v[166:169], v[216:219], v[24:27]
	v_mfma_f32_16x16x32_bf16 v[20:23], v[176:179], v[216:219], v[20:23]
	v_mfma_f32_16x16x32_bf16 v[8:11], v[166:169], v[224:227], v[8:11]
	v_mfma_f32_16x16x32_bf16 v[4:7], v[176:179], v[224:227], v[4:7]
	v_mfma_f32_16x16x32_bf16 v[40:43], v[172:175], v[204:207], v[40:43]
	v_mfma_f32_16x16x32_bf16 v[36:39], v[180:183], v[204:207], v[36:39]
	v_mfma_f32_16x16x32_bf16 v[32:35], v[172:175], v[212:215], v[32:35]
	v_mfma_f32_16x16x32_bf16 v[28:31], v[180:183], v[212:215], v[28:31]
	v_mfma_f32_16x16x32_bf16 v[24:27], v[172:175], v[220:223], v[24:27]
	v_mfma_f32_16x16x32_bf16 v[20:23], v[180:183], v[220:223], v[20:23]
	v_mfma_f32_16x16x32_bf16 v[8:11], v[172:175], v[238:241], v[8:11]
	v_mfma_f32_16x16x32_bf16 v[4:7], v[180:183], v[238:241], v[4:7]
	v_mfma_f32_16x16x32_bf16 v[96:99], v[184:187], v[200:203], v[96:99]
	v_mfma_f32_16x16x32_bf16 v[92:95], v[192:195], v[200:203], v[92:95]
	v_mfma_f32_16x16x32_bf16 v[88:91], v[184:187], v[208:211], v[88:91]
	v_mfma_f32_16x16x32_bf16 v[84:87], v[192:195], v[208:211], v[84:87]
	v_mfma_f32_16x16x32_bf16 v[80:83], v[184:187], v[216:219], v[80:83]
	v_mfma_f32_16x16x32_bf16 v[76:79], v[192:195], v[216:219], v[76:79]
	v_mfma_f32_16x16x32_bf16 v[16:19], v[184:187], v[224:227], v[16:19]
	v_mfma_f32_16x16x32_bf16 v[12:15], v[192:195], v[224:227], v[12:15]
	v_mfma_f32_16x16x32_bf16 v[96:99], v[188:191], v[204:207], v[96:99]
	v_mfma_f32_16x16x32_bf16 v[92:95], v[196:199], v[204:207], v[92:95]
	v_mfma_f32_16x16x32_bf16 v[88:91], v[188:191], v[212:215], v[88:91]
	v_mfma_f32_16x16x32_bf16 v[84:87], v[196:199], v[212:215], v[84:87]
	v_mfma_f32_16x16x32_bf16 v[80:83], v[188:191], v[220:223], v[80:83]
	v_mfma_f32_16x16x32_bf16 v[76:79], v[196:199], v[220:223], v[76:79]
	v_mfma_f32_16x16x32_bf16 v[16:19], v[188:191], v[238:241], v[16:19]
	v_mfma_f32_16x16x32_bf16 v[12:15], v[196:199], v[238:241], v[12:15]
	s_barrier
	s_add_i32 s54, s54, 2
	s_add_u32 s2, s2, 0x100
	s_addc_u32 s3, s3, 0
	s_add_u32 s52, s52, 0x100
	s_addc_u32 s53, s53, 0
	s_cmp_gt_u32 s54, 13
	s_cbranch_scc0 .LBB0_293
	s_branch .Lpeel_exit1
	.p2align	6

; #define PG8_STAGE(bufoff, gbase, voff) do { _Pragma("unroll") for (int _i = 0; _i < 2; ++_i) \
;         __builtin_amdgcn_global_load_lds((const unsigned*)((const char*)(gbase) + (voff)[_i]), (PG8_LAS unsigned*)(lds + (bufoff) + ldsw + _i * 8192), 16, 0, 0); } while (0)
; #define PG8_LDA(dst, b, h) do { _Pragma("unroll") for (int m = 0; m < 4; ++m) _Pragma("unroll") for (int k = 0; k < 2; ++k) dst[m][k] = *(const PG8_LAS bf16x8*)(lds + PG8_SA(b, h) + aoff + m * 2048 + k * 1024); } while (0)
; #define PG8_LDB(dst, b, h) do { _Pragma("unroll") for (int n = 0; n < 2; ++n) _Pragma("unroll") for (int k = 0; k < 2; ++k) dst[n][k] = *(const PG8_LAS bf16x8*)(lds + PG8_SB(b, h) + boff + n * 2048 + k * 1024); } while (0)
; #define PG8_MMA(ai, bj, At, Bt) do { __builtin_amdgcn_s_setprio(1); _Pragma("unroll") for (int m = 0; m < 4; ++m) _Pragma("unroll") for (int n = 0; n < 2; ++n) _Pragma("unroll") for (int k = 0; k < 2; ++k) \
;         acc[ai][bj][m][n] = __builtin_amdgcn_mfma_f32_16x16x32_bf16(Bt[n][k], At[m][k], acc[ai][bj][m][n], 0, 0, 0); __builtin_amdgcn_s_setprio(0); } while (0)
; template <class Epi, class Sched, bool ALIGN_EPI = false, bool SP2 = false>
; __device__ __forceinline__ void gemm_phase(PG8_LAS unsigned char* lds, const Gemm g, const Sched& S, const Epi& E, const int tid) {
;     ...
;     for (;;) {
;         const bool has_next = S.next(ui + 1, nxt);
;         const char* nA = has_next ? (const char*)g.A + (size_t)nxt.pm * tstep : cA; const char* nB = has_next ? (const char*)g.Bt + (size_t)nxt.pn * tstep : cB;
;         for (int t = 0; t < nt; t += 2) {
;             const bool last = (t == nt - 2);
;             const char* a1 = cA + (size_t)(t + 1) * kstep;
;             const char* a2 = last ? nA : cA + (size_t)(t + 2) * kstep; const char* b2 = last ? nB : cB + (size_t)(t + 2) * kstep;
;             const char* a3 = a2 + kstep; const char* b3 = b2 + kstep;
;             if (last && has_next) S.a_ready(nxt);
;             if constexpr (SP2) {
;             PG8_LDB(B0, 0, 0); PG8_LDB(B1, 0, 1); PG8_SCHED; PG8_LDA(At, 0, 0); PG8_STAGE(PG8_SA(1, 1), a1 + hstep, voffA);
;             PG8_WAIT_V(8); PG8_WAIT_L(0); PG8_BAR; PG8_MMA(0, 0, At, B0); PG8_MMA(0, 1, At, B1); PG8_BAR; PG8_SCHED;
;             PG8_LDA(At, 0, 1); PG8_STAGE(PG8_SB(0, 0), b2, voffB); PG8_STAGE(PG8_SB(0, 1), b2 + hstep, voffB); PG8_STAGE(PG8_SA(0, 0), a2, voffA);
.LBB0_475:
	s_add_u32 s6, s6, 0x80
	s_addc_u32 s7, s7, 0
	s_add_u32 s78, s58, 0x100
	v_mov_b32_e32 v4, 0
	s_addc_u32 s79, s59, 0
	s_mov_b32 s58, 0
	s_add_i32 s80, s58, 2
	s_add_u32 s81, s6, 0x80
	s_addc_u32 s59, s7, 0
	s_add_i32 s87, 0, 0x10000
	s_cmp_eq_u32 s70, s58
	s_cselect_b32 s59, s55, s59
	s_cselect_b32 s58, s54, s81
	v_add_u32_e32 v144, s87, v184
	s_cselect_b32 s83, s57, s79
	s_cselect_b32 s82, s56, s78
	s_add_i32 s81, 0, 0x14000
	ds_read_b128 v[132:135], v144
	ds_read_b128 v[136:139], v144 offset:1024
	ds_read_b128 v[140:143], v144 offset:2048
	ds_read_b128 v[174:177], v144 offset:3072
	v_add_u32_e32 v144, s81, v184
	ds_read_b128 v[178:181], v144
	ds_read_b128 v[188:191], v144 offset:1024
	ds_read_b128 v[192:195], v144 offset:2048
	ds_read_b128 v[196:199], v144 offset:3072
	v_lshl_add_u64 v[144:145], s[6:7], 0, v[170:171]
	s_add_i32 m0, s62, 0xc000
	ds_read_b128 v[200:203], v186
	ds_read_b128 v[204:207], v186 offset:1024
	ds_read_b128 v[208:211], v186 offset:2048
	ds_read_b128 v[212:215], v186 offset:3072
	ds_read_b128 v[216:219], v186 offset:4096
	ds_read_b128 v[220:223], v186 offset:5120
	ds_read_b128 v[224:227], v186 offset:6144
	ds_read_b128 v[238:241], v186 offset:7168
	global_load_lds_dwordx4 v[144:145], off
	v_lshl_add_u64 v[144:145], s[6:7], 0, v[172:173]
	s_add_i32 m0, s62, 0xe000
	s_nop 0
	global_load_lds_dwordx4 v[144:145], off
	s_waitcnt vmcnt(8)
	s_waitcnt lgkmcnt(0)
	s_barrier
	s_waitcnt lgkmcnt(0)
	v_mfma_f32_16x16x32_bf16 v[128:131], v[132:135], v[200:203], 0
	v_mfma_f32_16x16x32_bf16 v[124:127], v[140:143], v[200:203], 0
	v_mfma_f32_16x16x32_bf16 v[112:115], v[132:135], v[208:211], 0
	v_mfma_f32_16x16x32_bf16 v[108:111], v[140:143], v[208:211], 0
	v_mfma_f32_16x16x32_bf16 v[96:99], v[132:135], v[216:219], 0
	v_mfma_f32_16x16x32_bf16 v[92:95], v[140:143], v[216:219], 0
	v_mfma_f32_16x16x32_bf16 v[80:83], v[132:135], v[224:227], 0
	v_mfma_f32_16x16x32_bf16 v[76:79], v[140:143], v[224:227], 0
	v_mfma_f32_16x16x32_bf16 v[128:131], v[136:139], v[204:207], v[128:131]
	v_mfma_f32_16x16x32_bf16 v[124:127], v[174:177], v[204:207], v[124:127]
	v_mfma_f32_16x16x32_bf16 v[112:115], v[136:139], v[212:215], v[112:115]
	v_mfma_f32_16x16x32_bf16 v[108:111], v[174:177], v[212:215], v[108:111]
	v_mfma_f32_16x16x32_bf16 v[96:99], v[136:139], v[220:223], v[96:99]
	v_mfma_f32_16x16x32_bf16 v[92:95], v[174:177], v[220:223], v[92:95]
	v_mfma_f32_16x16x32_bf16 v[80:83], v[136:139], v[238:241], v[80:83]
	v_mfma_f32_16x16x32_bf16 v[76:79], v[174:177], v[238:241], v[76:79]
	v_mfma_f32_16x16x32_bf16 v[120:123], v[178:181], v[200:203], 0
	v_mfma_f32_16x16x32_bf16 v[116:119], v[192:195], v[200:203], 0
	v_mfma_f32_16x16x32_bf16 v[104:107], v[178:181], v[208:211], 0
	v_mfma_f32_16x16x32_bf16 v[100:103], v[192:195], v[208:211], 0
	v_mfma_f32_16x16x32_bf16 v[88:91], v[178:181], v[216:219], 0
	v_mfma_f32_16x16x32_bf16 v[84:87], v[192:195], v[216:219], 0
	v_mfma_f32_16x16x32_bf16 v[72:75], v[178:181], v[224:227], 0
	v_mfma_f32_16x16x32_bf16 v[68:71], v[192:195], v[224:227], 0
	v_mfma_f32_16x16x32_bf16 v[120:123], v[188:191], v[204:207], v[120:123]
	v_mfma_f32_16x16x32_bf16 v[116:119], v[196:199], v[204:207], v[116:119]
	v_mfma_f32_16x16x32_bf16 v[104:107], v[188:191], v[212:215], v[104:107]
	v_mfma_f32_16x16x32_bf16 v[100:103], v[196:199], v[212:215], v[100:103]
	v_mfma_f32_16x16x32_bf16 v[88:91], v[188:191], v[220:223], v[88:91]
	v_mfma_f32_16x16x32_bf16 v[84:87], v[196:199], v[220:223], v[84:87]
	v_mfma_f32_16x16x32_bf16 v[72:75], v[188:191], v[238:241], v[72:75]
	v_mfma_f32_16x16x32_bf16 v[68:71], v[196:199], v[238:241], v[68:71]
	s_barrier
	s_add_i32 s87, s87, s61
	v_lshl_add_u64 v[144:145], s[82:83], 0, v[146:147]
	s_mov_b32 m0, s87
	ds_read_b128 v[200:203], v186 offset:16384
	ds_read_b128 v[204:207], v186 offset:17408
	ds_read_b128 v[208:211], v186 offset:18432
	ds_read_b128 v[212:215], v186 offset:19456
	ds_read_b128 v[216:219], v186 offset:20480
	ds_read_b128 v[220:223], v186 offset:21504
	ds_read_b128 v[224:227], v186 offset:22528
	ds_read_b128 v[238:241], v186 offset:23552
	global_load_lds_dwordx4 v[144:145], off
	s_add_i32 m0, s87, 0x2000
	v_lshl_add_u64 v[242:243], s[82:83], 0, v[168:169]
	s_add_u32 s82, s82, s14
	s_addc_u32 s83, s83, 0
	s_add_i32 s81, s81, s61
	global_load_lds_dwordx4 v[242:243], off
	v_lshl_add_u64 v[244:245], s[82:83], 0, v[146:147]
	s_mov_b32 m0, s81
	v_lshl_add_u64 v[246:247], s[82:83], 0, v[168:169]
	global_load_lds_dwordx4 v[244:245], off
	s_add_i32 m0, s81, 0x2000
	v_lshl_add_u64 v[248:249], s[58:59], 0, v[0:1]
	global_load_lds_dwordx4 v[246:247], off
	s_mov_b32 m0, s62
	v_lshl_add_u64 v[148:149], s[58:59], 0, v[166:167]
	global_load_lds_dwordx4 v[248:249], off
	s_mov_b32 m0, s63
	s_nop 0
	global_load_lds_dwordx4 v[148:149], off
	s_waitcnt vmcnt(8)
	s_waitcnt lgkmcnt(0)
	s_barrier
; #define PG8_STAGE(bufoff, gbase, voff) do { _Pragma("unroll") for (int _i = 0; _i < 2; ++_i) \
;         __builtin_amdgcn_global_load_lds((const unsigned*)((const char*)(gbase) + (voff)[_i]), (PG8_LAS unsigned*)(lds + (bufoff) + ldsw + _i * 8192), 16, 0, 0); } while (0)
; #define PG8_LDA(dst, b, h) do { _Pragma("unroll") for (int m = 0; m < 4; ++m) _Pragma("unroll") for (int k = 0; k < 2; ++k) dst[m][k] = *(const PG8_LAS bf16x8*)(lds + PG8_SA(b, h) + aoff + m * 2048 + k * 1024); } while (0)
; #define PG8_LDB(dst, b, h) do { _Pragma("unroll") for (int n = 0; n < 2; ++n) _Pragma("unroll") for (int k = 0; k < 2; ++k) dst[n][k] = *(const PG8_LAS bf16x8*)(lds + PG8_SB(b, h) + boff + n * 2048 + k * 1024); } while (0)
; #define PG8_MMA(ai, bj, At, Bt) do { __builtin_amdgcn_s_setprio(1); _Pragma("unroll") for (int m = 0; m < 4; ++m) _Pragma("unroll") for (int n = 0; n < 2; ++n) _Pragma("unroll") for (int k = 0; k < 2; ++k) \
;         acc[ai][bj][m][n] = __builtin_amdgcn_mfma_f32_16x16x32_bf16(Bt[n][k], At[m][k], acc[ai][bj][m][n], 0, 0, 0); __builtin_amdgcn_s_setprio(0); } while (0)
; #define PG8_WAIT_V(n) asm volatile("s_waitcnt vmcnt(" #n ")" ::: "memory")
; #define PG8_WAIT_L(n) asm volatile("s_waitcnt lgkmcnt(" #n ")" ::: "memory")
; #define PG8_BAR __builtin_amdgcn_s_barrier()
; #define PG8_SCHED __builtin_amdgcn_sched_barrier(0)
; template <class Epi, class Sched, bool ALIGN_EPI = false, bool SP2 = false>
; __device__ __forceinline__ void gemm_phase(PG8_LAS unsigned char* lds, const Gemm g, const Sched& S, const Epi& E, const int tid) {
;     ...
;             PG8_WAIT_V(8); PG8_WAIT_L(0); PG8_BAR; PG8_MMA(1, 0, At, B0); PG8_MMA(1, 1, At, B1); PG8_BAR; PG8_SCHED;
;             PG8_LDB(B0, 1, 0); PG8_LDB(B1, 1, 1); PG8_SCHED; PG8_LDA(At, 1, 0); PG8_STAGE(PG8_SA(0, 1), a2 + hstep, voffA);
;             PG8_WAIT_V(8); PG8_WAIT_L(0); PG8_BAR; PG8_MMA(0, 0, At, B0); PG8_MMA(0, 1, At, B1); PG8_BAR; PG8_SCHED;
	s_waitcnt lgkmcnt(0)
	v_mfma_f32_16x16x32_bf16 v[64:67], v[132:135], v[200:203], 0
	v_mfma_f32_16x16x32_bf16 v[60:63], v[140:143], v[200:203], 0
	v_mfma_f32_16x16x32_bf16 v[48:51], v[132:135], v[208:211], 0
	v_mfma_f32_16x16x32_bf16 v[44:47], v[140:143], v[208:211], 0
	v_mfma_f32_16x16x32_bf16 v[32:35], v[132:135], v[216:219], 0
	v_mfma_f32_16x16x32_bf16 v[28:31], v[140:143], v[216:219], 0
	v_mfma_f32_16x16x32_bf16 v[16:19], v[132:135], v[224:227], 0
	v_mfma_f32_16x16x32_bf16 v[12:15], v[140:143], v[224:227], 0
	v_mfma_f32_16x16x32_bf16 v[64:67], v[136:139], v[204:207], v[64:67]
	v_mfma_f32_16x16x32_bf16 v[60:63], v[174:177], v[204:207], v[60:63]
	v_mfma_f32_16x16x32_bf16 v[48:51], v[136:139], v[212:215], v[48:51]
	v_mfma_f32_16x16x32_bf16 v[44:47], v[174:177], v[212:215], v[44:47]
	v_mfma_f32_16x16x32_bf16 v[32:35], v[136:139], v[220:223], v[32:35]
	v_mfma_f32_16x16x32_bf16 v[28:31], v[174:177], v[220:223], v[28:31]
	v_mfma_f32_16x16x32_bf16 v[16:19], v[136:139], v[238:241], v[16:19]
	v_mfma_f32_16x16x32_bf16 v[12:15], v[174:177], v[238:241], v[12:15]
	v_mfma_f32_16x16x32_bf16 v[56:59], v[178:181], v[200:203], 0
	v_mfma_f32_16x16x32_bf16 v[52:55], v[192:195], v[200:203], 0
	v_mfma_f32_16x16x32_bf16 v[40:43], v[178:181], v[208:211], 0
	v_mfma_f32_16x16x32_bf16 v[36:39], v[192:195], v[208:211], 0
	v_mfma_f32_16x16x32_bf16 v[24:27], v[178:181], v[216:219], 0
	v_mfma_f32_16x16x32_bf16 v[20:23], v[192:195], v[216:219], 0
	v_mfma_f32_16x16x32_bf16 v[8:11], v[178:181], v[224:227], 0
	v_mfma_f32_16x16x32_bf16 v[4:7], v[192:195], v[224:227], 0
	v_mfma_f32_16x16x32_bf16 v[56:59], v[188:191], v[204:207], v[56:59]
	v_mfma_f32_16x16x32_bf16 v[52:55], v[196:199], v[204:207], v[52:55]
	v_mfma_f32_16x16x32_bf16 v[40:43], v[188:191], v[212:215], v[40:43]
	v_mfma_f32_16x16x32_bf16 v[36:39], v[196:199], v[212:215], v[36:39]
	v_mfma_f32_16x16x32_bf16 v[24:27], v[188:191], v[220:223], v[24:27]
	v_mfma_f32_16x16x32_bf16 v[20:23], v[196:199], v[220:223], v[20:23]
	v_mfma_f32_16x16x32_bf16 v[8:11], v[188:191], v[238:241], v[8:11]
	v_mfma_f32_16x16x32_bf16 v[4:7], v[196:199], v[238:241], v[4:7]
	s_barrier
	s_add_i32 s81, 0, 0x18000
	v_add_u32_e32 v150, s81, v184
	s_add_i32 s82, 0, 0x1c000
	ds_read_b128 v[132:135], v150
	ds_read_b128 v[136:139], v150 offset:1024
	ds_read_b128 v[140:143], v150 offset:2048
	ds_read_b128 v[174:177], v150 offset:3072
	v_add_u32_e32 v150, s82, v184
	ds_read_b128 v[178:181], v150
	ds_read_b128 v[188:191], v150 offset:1024
	ds_read_b128 v[192:195], v150 offset:2048
	ds_read_b128 v[196:199], v150 offset:3072
	s_add_u32 s58, s58, s14
	s_addc_u32 s59, s59, 0
	s_mov_b32 m0, s64
	v_lshl_add_u64 v[150:151], s[58:59], 0, v[0:1]
	ds_read_b128 v[200:203], v186 offset:32768
	ds_read_b128 v[204:207], v186 offset:33792
	ds_read_b128 v[208:211], v186 offset:34816
	ds_read_b128 v[212:215], v186 offset:35840
	ds_read_b128 v[216:219], v186 offset:36864
	ds_read_b128 v[220:223], v186 offset:37888
	ds_read_b128 v[224:227], v186 offset:38912
	ds_read_b128 v[238:241], v186 offset:39936
	global_load_lds_dwordx4 v[150:151], off
	v_lshl_add_u64 v[150:151], s[58:59], 0, v[166:167]
	s_mov_b32 m0, s65
	s_nop 0
	global_load_lds_dwordx4 v[150:151], off
	s_waitcnt vmcnt(8)
	s_waitcnt lgkmcnt(0)
	s_barrier
	s_waitcnt lgkmcnt(0)
	v_mfma_f32_16x16x32_bf16 v[128:131], v[132:135], v[200:203], v[128:131]
	v_mfma_f32_16x16x32_bf16 v[124:127], v[140:143], v[200:203], v[124:127]
	v_mfma_f32_16x16x32_bf16 v[112:115], v[132:135], v[208:211], v[112:115]
	v_mfma_f32_16x16x32_bf16 v[108:111], v[140:143], v[208:211], v[108:111]
	v_mfma_f32_16x16x32_bf16 v[96:99], v[132:135], v[216:219], v[96:99]
	v_mfma_f32_16x16x32_bf16 v[92:95], v[140:143], v[216:219], v[92:95]
	v_mfma_f32_16x16x32_bf16 v[80:83], v[132:135], v[224:227], v[80:83]
	v_mfma_f32_16x16x32_bf16 v[76:79], v[140:143], v[224:227], v[76:79]
	v_mfma_f32_16x16x32_bf16 v[128:131], v[136:139], v[204:207], v[128:131]
	v_mfma_f32_16x16x32_bf16 v[124:127], v[174:177], v[204:207], v[124:127]
	v_mfma_f32_16x16x32_bf16 v[112:115], v[136:139], v[212:215], v[112:115]
	v_mfma_f32_16x16x32_bf16 v[108:111], v[174:177], v[212:215], v[108:111]
	v_mfma_f32_16x16x32_bf16 v[96:99], v[136:139], v[220:223], v[96:99]
	v_mfma_f32_16x16x32_bf16 v[92:95], v[174:177], v[220:223], v[92:95]
	v_mfma_f32_16x16x32_bf16 v[80:83], v[136:139], v[238:241], v[80:83]
	v_mfma_f32_16x16x32_bf16 v[76:79], v[174:177], v[238:241], v[76:79]
	v_mfma_f32_16x16x32_bf16 v[120:123], v[178:181], v[200:203], v[120:123]
	v_mfma_f32_16x16x32_bf16 v[116:119], v[192:195], v[200:203], v[116:119]
	v_mfma_f32_16x16x32_bf16 v[104:107], v[178:181], v[208:211], v[104:107]
	v_mfma_f32_16x16x32_bf16 v[100:103], v[192:195], v[208:211], v[100:103]
	v_mfma_f32_16x16x32_bf16 v[88:91], v[178:181], v[216:219], v[88:91]
	v_mfma_f32_16x16x32_bf16 v[84:87], v[192:195], v[216:219], v[84:87]
	v_mfma_f32_16x16x32_bf16 v[72:75], v[178:181], v[224:227], v[72:75]
	v_mfma_f32_16x16x32_bf16 v[68:71], v[192:195], v[224:227], v[68:71]
	v_mfma_f32_16x16x32_bf16 v[120:123], v[188:191], v[204:207], v[120:123]
	v_mfma_f32_16x16x32_bf16 v[116:119], v[196:199], v[204:207], v[116:119]
	v_mfma_f32_16x16x32_bf16 v[104:107], v[188:191], v[212:215], v[104:107]
	v_mfma_f32_16x16x32_bf16 v[100:103], v[196:199], v[212:215], v[100:103]
	v_mfma_f32_16x16x32_bf16 v[88:91], v[188:191], v[220:223], v[88:91]
	v_mfma_f32_16x16x32_bf16 v[84:87], v[196:199], v[220:223], v[84:87]
	v_mfma_f32_16x16x32_bf16 v[72:75], v[188:191], v[238:241], v[72:75]
	v_mfma_f32_16x16x32_bf16 v[68:71], v[196:199], v[238:241], v[68:71]
	s_barrier
; #define PG8_STAGE(bufoff, gbase, voff) do { _Pragma("unroll") for (int _i = 0; _i < 2; ++_i) \
;         __builtin_amdgcn_global_load_lds((const unsigned*)((const char*)(gbase) + (voff)[_i]), (PG8_LAS unsigned*)(lds + (bufoff) + ldsw + _i * 8192), 16, 0, 0); } while (0)
; #define PG8_LDA(dst, b, h) do { _Pragma("unroll") for (int m = 0; m < 4; ++m) _Pragma("unroll") for (int k = 0; k < 2; ++k) dst[m][k] = *(const PG8_LAS bf16x8*)(lds + PG8_SA(b, h) + aoff + m * 2048 + k * 1024); } while (0)
; #define PG8_MMA(ai, bj, At, Bt) do { __builtin_amdgcn_s_setprio(1); _Pragma("unroll") for (int m = 0; m < 4; ++m) _Pragma("unroll") for (int n = 0; n < 2; ++n) _Pragma("unroll") for (int k = 0; k < 2; ++k) \
;         acc[ai][bj][m][n] = __builtin_amdgcn_mfma_f32_16x16x32_bf16(Bt[n][k], At[m][k], acc[ai][bj][m][n], 0, 0, 0); __builtin_amdgcn_s_setprio(0); } while (0)
; #define PG8_WAIT_V(n) asm volatile("s_waitcnt vmcnt(" #n ")" ::: "memory")
; #define PG8_WAIT_L(n) asm volatile("s_waitcnt lgkmcnt(" #n ")" ::: "memory")
; #define PG8_BAR __builtin_amdgcn_s_barrier()
; #define PG8_SCHED __builtin_amdgcn_sched_barrier(0)
; template <class Epi, class Sched, bool ALIGN_EPI = false, bool SP2 = false>
; __device__ __forceinline__ void gemm_phase(PG8_LAS unsigned char* lds, const Gemm g, const Sched& S, const Epi& E, const int tid) {
;     ...
;             PG8_LDA(At, 1, 1); PG8_STAGE(PG8_SB(1, 0), b3, voffB); PG8_STAGE(PG8_SB(1, 1), b3 + hstep, voffB); PG8_STAGE(PG8_SA(1, 0), a3, voffA);
;             PG8_WAIT_V(8); PG8_WAIT_L(0); PG8_BAR; PG8_MMA(1, 0, At, B0); PG8_MMA(1, 1, At, B1); PG8_BAR; PG8_SCHED;
	s_add_i32 s58, s81, s61
	v_lshl_add_u64 v[144:145], v[144:145], 0, s[0:1]
	s_mov_b32 m0, s58
	ds_read_b128 v[200:203], v186 offset:49152
	ds_read_b128 v[204:207], v186 offset:50176
	ds_read_b128 v[208:211], v186 offset:51200
	ds_read_b128 v[212:215], v186 offset:52224
	ds_read_b128 v[216:219], v186 offset:53248
	ds_read_b128 v[220:223], v186 offset:54272
	ds_read_b128 v[224:227], v186 offset:55296
	ds_read_b128 v[238:241], v186 offset:56320
	global_load_lds_dwordx4 v[144:145], off
	v_lshl_add_u64 v[144:145], v[242:243], 0, s[0:1]
	s_add_i32 m0, s58, 0x2000
	s_add_i32 s58, s82, s61
	global_load_lds_dwordx4 v[144:145], off
	v_lshl_add_u64 v[144:145], v[244:245], 0, s[0:1]
	s_mov_b32 m0, s58
	s_nop 0
	global_load_lds_dwordx4 v[144:145], off
	v_lshl_add_u64 v[144:145], v[246:247], 0, s[0:1]
	s_add_i32 m0, s58, 0x2000
	s_nop 0
	global_load_lds_dwordx4 v[144:145], off
	v_lshl_add_u64 v[144:145], v[248:249], 0, s[0:1]
	s_mov_b32 m0, s66
	s_nop 0
	global_load_lds_dwordx4 v[144:145], off
	v_lshl_add_u64 v[144:145], v[148:149], 0, s[0:1]
	s_mov_b32 m0, s67
	s_nop 0
	global_load_lds_dwordx4 v[144:145], off
	s_waitcnt vmcnt(8)
	s_waitcnt lgkmcnt(0)
	s_barrier
	s_waitcnt lgkmcnt(0)
	v_mfma_f32_16x16x32_bf16 v[64:67], v[132:135], v[200:203], v[64:67]
	v_mfma_f32_16x16x32_bf16 v[60:63], v[140:143], v[200:203], v[60:63]
	v_mfma_f32_16x16x32_bf16 v[48:51], v[132:135], v[208:211], v[48:51]
	v_mfma_f32_16x16x32_bf16 v[44:47], v[140:143], v[208:211], v[44:47]
	v_mfma_f32_16x16x32_bf16 v[32:35], v[132:135], v[216:219], v[32:35]
	v_mfma_f32_16x16x32_bf16 v[28:31], v[140:143], v[216:219], v[28:31]
	v_mfma_f32_16x16x32_bf16 v[16:19], v[132:135], v[224:227], v[16:19]
	v_mfma_f32_16x16x32_bf16 v[12:15], v[140:143], v[224:227], v[12:15]
	v_mfma_f32_16x16x32_bf16 v[64:67], v[136:139], v[204:207], v[64:67]
	v_mfma_f32_16x16x32_bf16 v[60:63], v[174:177], v[204:207], v[60:63]
	v_mfma_f32_16x16x32_bf16 v[48:51], v[136:139], v[212:215], v[48:51]
	v_mfma_f32_16x16x32_bf16 v[44:47], v[174:177], v[212:215], v[44:47]
	v_mfma_f32_16x16x32_bf16 v[32:35], v[136:139], v[220:223], v[32:35]
	v_mfma_f32_16x16x32_bf16 v[28:31], v[174:177], v[220:223], v[28:31]
	v_mfma_f32_16x16x32_bf16 v[16:19], v[136:139], v[238:241], v[16:19]
	v_mfma_f32_16x16x32_bf16 v[12:15], v[174:177], v[238:241], v[12:15]
	v_mfma_f32_16x16x32_bf16 v[56:59], v[178:181], v[200:203], v[56:59]
	v_mfma_f32_16x16x32_bf16 v[52:55], v[192:195], v[200:203], v[52:55]
	v_mfma_f32_16x16x32_bf16 v[40:43], v[178:181], v[208:211], v[40:43]
	v_mfma_f32_16x16x32_bf16 v[36:39], v[192:195], v[208:211], v[36:39]
	v_mfma_f32_16x16x32_bf16 v[24:27], v[178:181], v[216:219], v[24:27]
	v_mfma_f32_16x16x32_bf16 v[20:23], v[192:195], v[216:219], v[20:23]
	v_mfma_f32_16x16x32_bf16 v[8:11], v[178:181], v[224:227], v[8:11]
	v_mfma_f32_16x16x32_bf16 v[4:7], v[192:195], v[224:227], v[4:7]
	v_mfma_f32_16x16x32_bf16 v[56:59], v[188:191], v[204:207], v[56:59]
	v_mfma_f32_16x16x32_bf16 v[52:55], v[196:199], v[204:207], v[52:55]
	v_mfma_f32_16x16x32_bf16 v[40:43], v[188:191], v[212:215], v[40:43]
	v_mfma_f32_16x16x32_bf16 v[36:39], v[196:199], v[212:215], v[36:39]
	v_mfma_f32_16x16x32_bf16 v[24:27], v[188:191], v[220:223], v[24:27]
	v_mfma_f32_16x16x32_bf16 v[20:23], v[196:199], v[220:223], v[20:23]
	v_mfma_f32_16x16x32_bf16 v[8:11], v[188:191], v[238:241], v[8:11]
	v_mfma_f32_16x16x32_bf16 v[4:7], v[196:199], v[238:241], v[4:7]
	s_barrier
	s_add_u32 s6, s6, 0x100
	s_addc_u32 s7, s7, 0
	s_add_u32 s78, s78, 0x100
	s_addc_u32 s79, s79, 0
	s_cmp_ge_u32 s80, s69
	s_mov_b32 s58, s80
	s_cbranch_scc0 .LBB0_476
	s_branch .Lpeel_exit2
	.p2align	6

; #define PG8_STAGE(bufoff, gbase, voff) do { _Pragma("unroll") for (int _i = 0; _i < 2; ++_i) \
;         __builtin_amdgcn_global_load_lds((const unsigned*)((const char*)(gbase) + (voff)[_i]), (PG8_LAS unsigned*)(lds + (bufoff) + ldsw + _i * 8192), 16, 0, 0); } while (0)
; #define PG8_LDA(dst, b, h) do { _Pragma("unroll") for (int m = 0; m < 4; ++m) _Pragma("unroll") for (int k = 0; k < 2; ++k) dst[m][k] = *(const PG8_LAS bf16x8*)(lds + PG8_SA(b, h) + aoff + m * 2048 + k * 1024); } while (0)
; #define PG8_LDB(dst, b, h) do { _Pragma("unroll") for (int n = 0; n < 2; ++n) _Pragma("unroll") for (int k = 0; k < 2; ++k) dst[n][k] = *(const PG8_LAS bf16x8*)(lds + PG8_SB(b, h) + boff + n * 2048 + k * 1024); } while (0)
; #define PG8_MMA(ai, bj, At, Bt) do { __builtin_amdgcn_s_setprio(1); _Pragma("unroll") for (int m = 0; m < 4; ++m) _Pragma("unroll") for (int n = 0; n < 2; ++n) _Pragma("unroll") for (int k = 0; k < 2; ++k) \
;         acc[ai][bj][m][n] = __builtin_amdgcn_mfma_f32_16x16x32_bf16(Bt[n][k], At[m][k], acc[ai][bj][m][n], 0, 0, 0); __builtin_amdgcn_s_setprio(0); } while (0)
; template <class Epi, class Sched, bool ALIGN_EPI = false, bool SP2 = false>
; __device__ __forceinline__ void gemm_phase(PG8_LAS unsigned char* lds, const Gemm g, const Sched& S, const Epi& E, const int tid) {
;     ...
;     for (;;) {
;         const bool has_next = S.next(ui + 1, nxt);
;         const char* nA = has_next ? (const char*)g.A + (size_t)nxt.pm * tstep : cA; const char* nB = has_next ? (const char*)g.Bt + (size_t)nxt.pn * tstep : cB;
;         for (int t = 0; t < nt; t += 2) {
;             const bool last = (t == nt - 2);
;             const char* a1 = cA + (size_t)(t + 1) * kstep;
;             const char* a2 = last ? nA : cA + (size_t)(t + 2) * kstep; const char* b2 = last ? nB : cB + (size_t)(t + 2) * kstep;
;             const char* a3 = a2 + kstep; const char* b3 = b2 + kstep;
;             if (last && has_next) S.a_ready(nxt);
;             if constexpr (SP2) {
;             PG8_LDB(B0, 0, 0); PG8_LDB(B1, 0, 1); PG8_SCHED; PG8_LDA(At, 0, 0); PG8_STAGE(PG8_SA(1, 1), a1 + hstep, voffA);
;             PG8_WAIT_V(8); PG8_WAIT_L(0); PG8_BAR; PG8_MMA(0, 0, At, B0); PG8_MMA(0, 1, At, B1); PG8_BAR; PG8_SCHED;
;             PG8_LDA(At, 0, 1); PG8_STAGE(PG8_SB(0, 0), b2, voffB); PG8_STAGE(PG8_SB(0, 1), b2 + hstep, voffB); PG8_STAGE(PG8_SA(0, 0), a2, voffA);
.LBB0_521:
	s_ashr_i32 s13, s12, 31
	s_lshl_b64 s[14:15], s[12:13], 19
	s_add_u32 s14, s26, s14
	s_addc_u32 s15, s27, s15
	s_and_b64 s[16:17], s[2:3], exec
	s_cselect_b32 s13, s15, s19
	s_cselect_b32 s47, s14, s18
	s_ashr_i32 s11, s10, 31
	s_lshl_b64 s[16:17], s[10:11], 19
	s_add_u32 s16, s34, s16
	s_addc_u32 s17, s36, s17
	s_and_b64 s[22:23], s[2:3], exec
	s_cselect_b32 s11, s17, s21
	s_cselect_b32 s48, s16, s20
	s_add_u32 s18, s18, 0x40080
	s_addc_u32 s19, s19, 0
	s_add_u32 s49, s20, 0x100
	v_mov_b32_e32 v4, 0
	s_addc_u32 s50, s21, 0
	s_mov_b32 s51, -2
	s_add_u32 s20, s18, 0xfffc0080
	s_addc_u32 s21, s19, -1
	s_add_i32 s52, 0, 0x10000
	s_cmp_eq_u32 s51, 12
	s_cselect_b32 s23, s13, s21
	s_cselect_b32 s22, s47, s20
	v_add_u32_e32 v148, s52, v146
	s_cselect_b32 s21, s11, s50
	s_cselect_b32 s20, s48, s49
	s_add_i32 s54, 0, 0x14000
	ds_read_b128 v[142:145], v148
	ds_read_b128 v[166:169], v148 offset:1024
	ds_read_b128 v[170:173], v148 offset:2048
	ds_read_b128 v[174:177], v148 offset:3072
	v_add_u32_e32 v148, s54, v146
	ds_read_b128 v[178:181], v148
	ds_read_b128 v[182:185], v148 offset:1024
	ds_read_b128 v[186:189], v148 offset:2048
	ds_read_b128 v[190:193], v148 offset:3072
	v_lshl_add_u64 v[226:227], s[18:19], 0, v[138:139]
	s_add_i32 m0, s38, 0xc000
	ds_read_b128 v[194:197], v153
	ds_read_b128 v[198:201], v153 offset:1024
	ds_read_b128 v[202:205], v153 offset:2048
	ds_read_b128 v[206:209], v153 offset:3072
	ds_read_b128 v[210:213], v153 offset:4096
	ds_read_b128 v[214:217], v153 offset:5120
	ds_read_b128 v[218:221], v153 offset:6144
	ds_read_b128 v[222:225], v153 offset:7168
	global_load_lds_dwordx4 v[226:227], off
	v_lshl_add_u64 v[226:227], s[18:19], 0, v[140:141]
	s_add_i32 m0, s38, 0xe000
	s_nop 0
	global_load_lds_dwordx4 v[226:227], off
	s_waitcnt vmcnt(8)
	s_waitcnt lgkmcnt(0)
	s_barrier
	s_waitcnt lgkmcnt(0)
	v_mfma_f32_16x16x32_bf16 v[128:131], v[142:145], v[194:197], 0
	v_mfma_f32_16x16x32_bf16 v[120:123], v[170:173], v[194:197], 0
	v_mfma_f32_16x16x32_bf16 v[112:115], v[142:145], v[202:205], 0
	v_mfma_f32_16x16x32_bf16 v[104:107], v[170:173], v[202:205], 0
	v_mfma_f32_16x16x32_bf16 v[96:99], v[142:145], v[210:213], 0
	v_mfma_f32_16x16x32_bf16 v[88:91], v[170:173], v[210:213], 0
	v_mfma_f32_16x16x32_bf16 v[80:83], v[142:145], v[218:221], 0
	v_mfma_f32_16x16x32_bf16 v[72:75], v[170:173], v[218:221], 0
	v_mfma_f32_16x16x32_bf16 v[128:131], v[166:169], v[198:201], v[128:131]
	v_mfma_f32_16x16x32_bf16 v[120:123], v[174:177], v[198:201], v[120:123]
	v_mfma_f32_16x16x32_bf16 v[112:115], v[166:169], v[206:209], v[112:115]
	v_mfma_f32_16x16x32_bf16 v[104:107], v[174:177], v[206:209], v[104:107]
	v_mfma_f32_16x16x32_bf16 v[96:99], v[166:169], v[214:217], v[96:99]
	v_mfma_f32_16x16x32_bf16 v[88:91], v[174:177], v[214:217], v[88:91]
	v_mfma_f32_16x16x32_bf16 v[80:83], v[166:169], v[222:225], v[80:83]
	v_mfma_f32_16x16x32_bf16 v[72:75], v[174:177], v[222:225], v[72:75]
	v_mfma_f32_16x16x32_bf16 v[124:127], v[178:181], v[194:197], 0
	v_mfma_f32_16x16x32_bf16 v[116:119], v[186:189], v[194:197], 0
	v_mfma_f32_16x16x32_bf16 v[108:111], v[178:181], v[202:205], 0
	v_mfma_f32_16x16x32_bf16 v[100:103], v[186:189], v[202:205], 0
	v_mfma_f32_16x16x32_bf16 v[92:95], v[178:181], v[210:213], 0
	v_mfma_f32_16x16x32_bf16 v[84:87], v[186:189], v[210:213], 0
	v_mfma_f32_16x16x32_bf16 v[76:79], v[178:181], v[218:221], 0
	v_mfma_f32_16x16x32_bf16 v[68:71], v[186:189], v[218:221], 0
	v_mfma_f32_16x16x32_bf16 v[124:127], v[182:185], v[198:201], v[124:127]
	v_mfma_f32_16x16x32_bf16 v[116:119], v[190:193], v[198:201], v[116:119]
	v_mfma_f32_16x16x32_bf16 v[108:111], v[182:185], v[206:209], v[108:111]
	v_mfma_f32_16x16x32_bf16 v[100:103], v[190:193], v[206:209], v[100:103]
	v_mfma_f32_16x16x32_bf16 v[92:95], v[182:185], v[214:217], v[92:95]
	v_mfma_f32_16x16x32_bf16 v[84:87], v[190:193], v[214:217], v[84:87]
	v_mfma_f32_16x16x32_bf16 v[76:79], v[182:185], v[222:225], v[76:79]
	v_mfma_f32_16x16x32_bf16 v[68:71], v[190:193], v[222:225], v[68:71]
	s_barrier
	s_add_i32 s52, s52, s37
	v_lshl_add_u64 v[226:227], s[20:21], 0, v[134:135]
	s_mov_b32 m0, s52
	ds_read_b128 v[194:197], v153 offset:16384
	ds_read_b128 v[198:201], v153 offset:17408
	ds_read_b128 v[202:205], v153 offset:18432
	ds_read_b128 v[206:209], v153 offset:19456
	ds_read_b128 v[210:213], v153 offset:20480
	ds_read_b128 v[214:217], v153 offset:21504
	ds_read_b128 v[218:221], v153 offset:22528
	ds_read_b128 v[222:225], v153 offset:23552
	global_load_lds_dwordx4 v[226:227], off
	s_add_i32 m0, s52, 0x2000
	s_add_u32 s52, s20, 0x40000
	v_lshl_add_u64 v[238:239], s[20:21], 0, v[0:1]
	s_addc_u32 s53, s21, 0
	s_add_i32 s54, s54, s37
	global_load_lds_dwordx4 v[238:239], off
	v_lshl_add_u64 v[240:241], s[52:53], 0, v[134:135]
	s_mov_b32 m0, s54
	v_lshl_add_u64 v[242:243], s[22:23], 0, v[132:133]
	global_load_lds_dwordx4 v[240:241], off
	v_lshl_add_u64 v[240:241], s[52:53], 0, v[0:1]
	s_add_i32 m0, s54, 0x2000
	s_nop 0
	global_load_lds_dwordx4 v[240:241], off
	v_lshl_add_u64 v[240:241], s[22:23], 0, v[136:137]
	s_mov_b32 m0, s38
	s_nop 0
	global_load_lds_dwordx4 v[240:241], off
	s_mov_b32 m0, s39
	s_nop 0
	global_load_lds_dwordx4 v[242:243], off
	s_waitcnt vmcnt(8)
	s_waitcnt lgkmcnt(0)
	s_barrier
; #define PG8_STAGE(bufoff, gbase, voff) do { _Pragma("unroll") for (int _i = 0; _i < 2; ++_i) \
;         __builtin_amdgcn_global_load_lds((const unsigned*)((const char*)(gbase) + (voff)[_i]), (PG8_LAS unsigned*)(lds + (bufoff) + ldsw + _i * 8192), 16, 0, 0); } while (0)
; #define PG8_LDA(dst, b, h) do { _Pragma("unroll") for (int m = 0; m < 4; ++m) _Pragma("unroll") for (int k = 0; k < 2; ++k) dst[m][k] = *(const PG8_LAS bf16x8*)(lds + PG8_SA(b, h) + aoff + m * 2048 + k * 1024); } while (0)
; #define PG8_LDB(dst, b, h) do { _Pragma("unroll") for (int n = 0; n < 2; ++n) _Pragma("unroll") for (int k = 0; k < 2; ++k) dst[n][k] = *(const PG8_LAS bf16x8*)(lds + PG8_SB(b, h) + boff + n * 2048 + k * 1024); } while (0)
; #define PG8_MMA(ai, bj, At, Bt) do { __builtin_amdgcn_s_setprio(1); _Pragma("unroll") for (int m = 0; m < 4; ++m) _Pragma("unroll") for (int n = 0; n < 2; ++n) _Pragma("unroll") for (int k = 0; k < 2; ++k) \
;         acc[ai][bj][m][n] = __builtin_amdgcn_mfma_f32_16x16x32_bf16(Bt[n][k], At[m][k], acc[ai][bj][m][n], 0, 0, 0); __builtin_amdgcn_s_setprio(0); } while (0)
; #define PG8_WAIT_V(n) asm volatile("s_waitcnt vmcnt(" #n ")" ::: "memory")
; #define PG8_WAIT_L(n) asm volatile("s_waitcnt lgkmcnt(" #n ")" ::: "memory")
; #define PG8_BAR __builtin_amdgcn_s_barrier()
; #define PG8_SCHED __builtin_amdgcn_sched_barrier(0)
; template <class Epi, class Sched, bool ALIGN_EPI = false, bool SP2 = false>
; __device__ __forceinline__ void gemm_phase(PG8_LAS unsigned char* lds, const Gemm g, const Sched& S, const Epi& E, const int tid) {
;     ...
;             PG8_WAIT_V(8); PG8_WAIT_L(0); PG8_BAR; PG8_MMA(1, 0, At, B0); PG8_MMA(1, 1, At, B1); PG8_BAR; PG8_SCHED;
;             PG8_LDB(B0, 1, 0); PG8_LDB(B1, 1, 1); PG8_SCHED; PG8_LDA(At, 1, 0); PG8_STAGE(PG8_SA(0, 1), a2 + hstep, voffA);
;             PG8_WAIT_V(8); PG8_WAIT_L(0); PG8_BAR; PG8_MMA(0, 0, At, B0); PG8_MMA(0, 1, At, B1); PG8_BAR; PG8_SCHED;
	s_waitcnt lgkmcnt(0)
	v_mfma_f32_16x16x32_bf16 v[64:67], v[142:145], v[194:197], 0
	v_mfma_f32_16x16x32_bf16 v[56:59], v[170:173], v[194:197], 0
	v_mfma_f32_16x16x32_bf16 v[48:51], v[142:145], v[202:205], 0
	v_mfma_f32_16x16x32_bf16 v[40:43], v[170:173], v[202:205], 0
	v_mfma_f32_16x16x32_bf16 v[32:35], v[142:145], v[210:213], 0
	v_mfma_f32_16x16x32_bf16 v[24:27], v[170:173], v[210:213], 0
	v_mfma_f32_16x16x32_bf16 v[16:19], v[142:145], v[218:221], 0
	v_mfma_f32_16x16x32_bf16 v[8:11], v[170:173], v[218:221], 0
	v_mfma_f32_16x16x32_bf16 v[64:67], v[166:169], v[198:201], v[64:67]
	v_mfma_f32_16x16x32_bf16 v[56:59], v[174:177], v[198:201], v[56:59]
	v_mfma_f32_16x16x32_bf16 v[48:51], v[166:169], v[206:209], v[48:51]
	v_mfma_f32_16x16x32_bf16 v[40:43], v[174:177], v[206:209], v[40:43]
	v_mfma_f32_16x16x32_bf16 v[32:35], v[166:169], v[214:217], v[32:35]
	v_mfma_f32_16x16x32_bf16 v[24:27], v[174:177], v[214:217], v[24:27]
	v_mfma_f32_16x16x32_bf16 v[16:19], v[166:169], v[222:225], v[16:19]
	v_mfma_f32_16x16x32_bf16 v[8:11], v[174:177], v[222:225], v[8:11]
	v_mfma_f32_16x16x32_bf16 v[60:63], v[178:181], v[194:197], 0
	v_mfma_f32_16x16x32_bf16 v[52:55], v[186:189], v[194:197], 0
	v_mfma_f32_16x16x32_bf16 v[44:47], v[178:181], v[202:205], 0
	v_mfma_f32_16x16x32_bf16 v[36:39], v[186:189], v[202:205], 0
	v_mfma_f32_16x16x32_bf16 v[28:31], v[178:181], v[210:213], 0
	v_mfma_f32_16x16x32_bf16 v[20:23], v[186:189], v[210:213], 0
	v_mfma_f32_16x16x32_bf16 v[12:15], v[178:181], v[218:221], 0
	v_mfma_f32_16x16x32_bf16 v[4:7], v[186:189], v[218:221], 0
	v_mfma_f32_16x16x32_bf16 v[60:63], v[182:185], v[198:201], v[60:63]
	v_mfma_f32_16x16x32_bf16 v[52:55], v[190:193], v[198:201], v[52:55]
	v_mfma_f32_16x16x32_bf16 v[44:47], v[182:185], v[206:209], v[44:47]
	v_mfma_f32_16x16x32_bf16 v[36:39], v[190:193], v[206:209], v[36:39]
	v_mfma_f32_16x16x32_bf16 v[28:31], v[182:185], v[214:217], v[28:31]
	v_mfma_f32_16x16x32_bf16 v[20:23], v[190:193], v[214:217], v[20:23]
	v_mfma_f32_16x16x32_bf16 v[12:15], v[182:185], v[222:225], v[12:15]
	v_mfma_f32_16x16x32_bf16 v[4:7], v[190:193], v[222:225], v[4:7]
	s_barrier
	s_add_i32 s52, 0, 0x18000
	v_add_u32_e32 v148, s52, v146
	s_add_i32 s53, 0, 0x1c000
	ds_read_b128 v[142:145], v148
	ds_read_b128 v[166:169], v148 offset:1024
	ds_read_b128 v[170:173], v148 offset:2048
	ds_read_b128 v[174:177], v148 offset:3072
	v_add_u32_e32 v148, s53, v146
	ds_read_b128 v[178:181], v148
	ds_read_b128 v[182:185], v148 offset:1024
	ds_read_b128 v[186:189], v148 offset:2048
	ds_read_b128 v[190:193], v148 offset:3072
	s_add_u32 s22, s22, 0x40000
	s_addc_u32 s23, s23, 0
	s_mov_b32 m0, s40
	v_lshl_add_u64 v[244:245], s[22:23], 0, v[136:137]
	ds_read_b128 v[194:197], v153 offset:32768
	ds_read_b128 v[198:201], v153 offset:33792
	ds_read_b128 v[202:205], v153 offset:34816
	ds_read_b128 v[206:209], v153 offset:35840
	ds_read_b128 v[210:213], v153 offset:36864
	ds_read_b128 v[214:217], v153 offset:37888
	ds_read_b128 v[218:221], v153 offset:38912
	ds_read_b128 v[222:225], v153 offset:39936
	global_load_lds_dwordx4 v[244:245], off
	v_lshl_add_u64 v[244:245], s[22:23], 0, v[132:133]
	s_mov_b32 m0, s41
	s_nop 0
	global_load_lds_dwordx4 v[244:245], off
	s_waitcnt vmcnt(8)
	s_waitcnt lgkmcnt(0)
	s_barrier
	s_waitcnt lgkmcnt(0)
	v_mfma_f32_16x16x32_bf16 v[128:131], v[142:145], v[194:197], v[128:131]
	v_mfma_f32_16x16x32_bf16 v[120:123], v[170:173], v[194:197], v[120:123]
	v_mfma_f32_16x16x32_bf16 v[112:115], v[142:145], v[202:205], v[112:115]
	v_mfma_f32_16x16x32_bf16 v[104:107], v[170:173], v[202:205], v[104:107]
	v_mfma_f32_16x16x32_bf16 v[96:99], v[142:145], v[210:213], v[96:99]
	v_mfma_f32_16x16x32_bf16 v[88:91], v[170:173], v[210:213], v[88:91]
	v_mfma_f32_16x16x32_bf16 v[80:83], v[142:145], v[218:221], v[80:83]
	v_mfma_f32_16x16x32_bf16 v[72:75], v[170:173], v[218:221], v[72:75]
	v_mfma_f32_16x16x32_bf16 v[128:131], v[166:169], v[198:201], v[128:131]
	v_mfma_f32_16x16x32_bf16 v[120:123], v[174:177], v[198:201], v[120:123]
	v_mfma_f32_16x16x32_bf16 v[112:115], v[166:169], v[206:209], v[112:115]
	v_mfma_f32_16x16x32_bf16 v[104:107], v[174:177], v[206:209], v[104:107]
	v_mfma_f32_16x16x32_bf16 v[96:99], v[166:169], v[214:217], v[96:99]
	v_mfma_f32_16x16x32_bf16 v[88:91], v[174:177], v[214:217], v[88:91]
	v_mfma_f32_16x16x32_bf16 v[80:83], v[166:169], v[222:225], v[80:83]
	v_mfma_f32_16x16x32_bf16 v[72:75], v[174:177], v[222:225], v[72:75]
	v_mfma_f32_16x16x32_bf16 v[124:127], v[178:181], v[194:197], v[124:127]
	v_mfma_f32_16x16x32_bf16 v[116:119], v[186:189], v[194:197], v[116:119]
	v_mfma_f32_16x16x32_bf16 v[108:111], v[178:181], v[202:205], v[108:111]
	v_mfma_f32_16x16x32_bf16 v[100:103], v[186:189], v[202:205], v[100:103]
	v_mfma_f32_16x16x32_bf16 v[92:95], v[178:181], v[210:213], v[92:95]
	v_mfma_f32_16x16x32_bf16 v[84:87], v[186:189], v[210:213], v[84:87]
	v_mfma_f32_16x16x32_bf16 v[76:79], v[178:181], v[218:221], v[76:79]
	v_mfma_f32_16x16x32_bf16 v[68:71], v[186:189], v[218:221], v[68:71]
	v_mfma_f32_16x16x32_bf16 v[124:127], v[182:185], v[198:201], v[124:127]
	v_mfma_f32_16x16x32_bf16 v[116:119], v[190:193], v[198:201], v[116:119]
	v_mfma_f32_16x16x32_bf16 v[108:111], v[182:185], v[206:209], v[108:111]
	v_mfma_f32_16x16x32_bf16 v[100:103], v[190:193], v[206:209], v[100:103]
	v_mfma_f32_16x16x32_bf16 v[92:95], v[182:185], v[214:217], v[92:95]
	v_mfma_f32_16x16x32_bf16 v[84:87], v[190:193], v[214:217], v[84:87]
	v_mfma_f32_16x16x32_bf16 v[76:79], v[182:185], v[222:225], v[76:79]
	v_mfma_f32_16x16x32_bf16 v[68:71], v[190:193], v[222:225], v[68:71]
	s_barrier
; #define PG8_STAGE(bufoff, gbase, voff) do { _Pragma("unroll") for (int _i = 0; _i < 2; ++_i) \
;         __builtin_amdgcn_global_load_lds((const unsigned*)((const char*)(gbase) + (voff)[_i]), (PG8_LAS unsigned*)(lds + (bufoff) + ldsw + _i * 8192), 16, 0, 0); } while (0)
; #define PG8_LDA(dst, b, h) do { _Pragma("unroll") for (int m = 0; m < 4; ++m) _Pragma("unroll") for (int k = 0; k < 2; ++k) dst[m][k] = *(const PG8_LAS bf16x8*)(lds + PG8_SA(b, h) + aoff + m * 2048 + k * 1024); } while (0)
; #define PG8_MMA(ai, bj, At, Bt) do { __builtin_amdgcn_s_setprio(1); _Pragma("unroll") for (int m = 0; m < 4; ++m) _Pragma("unroll") for (int n = 0; n < 2; ++n) _Pragma("unroll") for (int k = 0; k < 2; ++k) \
;         acc[ai][bj][m][n] = __builtin_amdgcn_mfma_f32_16x16x32_bf16(Bt[n][k], At[m][k], acc[ai][bj][m][n], 0, 0, 0); __builtin_amdgcn_s_setprio(0); } while (0)
; #define PG8_WAIT_V(n) asm volatile("s_waitcnt vmcnt(" #n ")" ::: "memory")
; #define PG8_WAIT_L(n) asm volatile("s_waitcnt lgkmcnt(" #n ")" ::: "memory")
; #define PG8_BAR __builtin_amdgcn_s_barrier()
; #define PG8_SCHED __builtin_amdgcn_sched_barrier(0)
; template <class Epi, class Sched, bool ALIGN_EPI = false, bool SP2 = false>
; __device__ __forceinline__ void gemm_phase(PG8_LAS unsigned char* lds, const Gemm g, const Sched& S, const Epi& E, const int tid) {
;     ...
;             PG8_LDA(At, 1, 1); PG8_STAGE(PG8_SB(1, 0), b3, voffB); PG8_STAGE(PG8_SB(1, 1), b3 + hstep, voffB); PG8_STAGE(PG8_SA(1, 0), a3, voffA);
;             PG8_WAIT_V(8); PG8_WAIT_L(0); PG8_BAR; PG8_MMA(1, 0, At, B0); PG8_MMA(1, 1, At, B1); PG8_BAR; PG8_SCHED;
	s_add_i32 s22, s52, s37
	v_lshl_add_u64 v[226:227], v[226:227], 0, s[0:1]
	s_mov_b32 m0, s22
	ds_read_b128 v[194:197], v153 offset:49152
	ds_read_b128 v[198:201], v153 offset:50176
	ds_read_b128 v[202:205], v153 offset:51200
	ds_read_b128 v[206:209], v153 offset:52224
	ds_read_b128 v[210:213], v153 offset:53248
	ds_read_b128 v[214:217], v153 offset:54272
	ds_read_b128 v[218:221], v153 offset:55296
	ds_read_b128 v[222:225], v153 offset:56320
	global_load_lds_dwordx4 v[226:227], off
	s_add_i32 m0, s22, 0x2000
	s_add_u32 s20, s20, 0x40080
	v_lshl_add_u64 v[226:227], v[238:239], 0, s[0:1]
	s_addc_u32 s21, s21, 0
	s_add_i32 s22, s53, s37
	global_load_lds_dwordx4 v[226:227], off
	v_lshl_add_u64 v[226:227], s[20:21], 0, v[134:135]
	s_mov_b32 m0, s22
	s_nop 0
	global_load_lds_dwordx4 v[226:227], off
	v_lshl_add_u64 v[226:227], s[20:21], 0, v[0:1]
	s_add_i32 m0, s22, 0x2000
	s_nop 0
	global_load_lds_dwordx4 v[226:227], off
	v_lshl_add_u64 v[226:227], v[240:241], 0, s[0:1]
	s_mov_b32 m0, s42
	s_nop 0
	global_load_lds_dwordx4 v[226:227], off
	v_lshl_add_u64 v[226:227], v[242:243], 0, s[0:1]
	s_mov_b32 m0, s43
	s_nop 0
	global_load_lds_dwordx4 v[226:227], off
	s_waitcnt vmcnt(8)
	s_waitcnt lgkmcnt(0)
	s_barrier
	s_waitcnt lgkmcnt(0)
	v_mfma_f32_16x16x32_bf16 v[64:67], v[142:145], v[194:197], v[64:67]
	v_mfma_f32_16x16x32_bf16 v[56:59], v[170:173], v[194:197], v[56:59]
	v_mfma_f32_16x16x32_bf16 v[48:51], v[142:145], v[202:205], v[48:51]
	v_mfma_f32_16x16x32_bf16 v[40:43], v[170:173], v[202:205], v[40:43]
	v_mfma_f32_16x16x32_bf16 v[32:35], v[142:145], v[210:213], v[32:35]
	v_mfma_f32_16x16x32_bf16 v[24:27], v[170:173], v[210:213], v[24:27]
	v_mfma_f32_16x16x32_bf16 v[16:19], v[142:145], v[218:221], v[16:19]
	v_mfma_f32_16x16x32_bf16 v[8:11], v[170:173], v[218:221], v[8:11]
	v_mfma_f32_16x16x32_bf16 v[64:67], v[166:169], v[198:201], v[64:67]
	v_mfma_f32_16x16x32_bf16 v[56:59], v[174:177], v[198:201], v[56:59]
	v_mfma_f32_16x16x32_bf16 v[48:51], v[166:169], v[206:209], v[48:51]
	v_mfma_f32_16x16x32_bf16 v[40:43], v[174:177], v[206:209], v[40:43]
	v_mfma_f32_16x16x32_bf16 v[32:35], v[166:169], v[214:217], v[32:35]
	v_mfma_f32_16x16x32_bf16 v[24:27], v[174:177], v[214:217], v[24:27]
	v_mfma_f32_16x16x32_bf16 v[16:19], v[166:169], v[222:225], v[16:19]
	v_mfma_f32_16x16x32_bf16 v[8:11], v[174:177], v[222:225], v[8:11]
	v_mfma_f32_16x16x32_bf16 v[60:63], v[178:181], v[194:197], v[60:63]
	v_mfma_f32_16x16x32_bf16 v[52:55], v[186:189], v[194:197], v[52:55]
	v_mfma_f32_16x16x32_bf16 v[44:47], v[178:181], v[202:205], v[44:47]
	v_mfma_f32_16x16x32_bf16 v[36:39], v[186:189], v[202:205], v[36:39]
	v_mfma_f32_16x16x32_bf16 v[28:31], v[178:181], v[210:213], v[28:31]
	v_mfma_f32_16x16x32_bf16 v[20:23], v[186:189], v[210:213], v[20:23]
	v_mfma_f32_16x16x32_bf16 v[12:15], v[178:181], v[218:221], v[12:15]
	v_mfma_f32_16x16x32_bf16 v[4:7], v[186:189], v[218:221], v[4:7]
	v_mfma_f32_16x16x32_bf16 v[60:63], v[182:185], v[198:201], v[60:63]
	v_mfma_f32_16x16x32_bf16 v[52:55], v[190:193], v[198:201], v[52:55]
	v_mfma_f32_16x16x32_bf16 v[44:47], v[182:185], v[206:209], v[44:47]
	v_mfma_f32_16x16x32_bf16 v[36:39], v[190:193], v[206:209], v[36:39]
	v_mfma_f32_16x16x32_bf16 v[28:31], v[182:185], v[214:217], v[28:31]
	v_mfma_f32_16x16x32_bf16 v[20:23], v[190:193], v[214:217], v[20:23]
	v_mfma_f32_16x16x32_bf16 v[12:15], v[182:185], v[222:225], v[12:15]
	v_mfma_f32_16x16x32_bf16 v[4:7], v[190:193], v[222:225], v[4:7]
	s_barrier
	s_add_i32 s51, s51, 2
	s_add_u32 s18, s18, 0x100
	s_addc_u32 s19, s19, 0
	s_add_u32 s49, s49, 0x100
	s_addc_u32 s50, s50, 0
	s_cmp_gt_u32 s51, 13
	s_cbranch_scc0 .LBB0_522
	s_branch .Lpeel_exit3
	.p2align	6

; #define PG8_STAGE(bufoff, gbase, voff) do { _Pragma("unroll") for (int _i = 0; _i < 2; ++_i) \
;         __builtin_amdgcn_global_load_lds((const unsigned*)((const char*)(gbase) + (voff)[_i]), (PG8_LAS unsigned*)(lds + (bufoff) + ldsw + _i * 8192), 16, 0, 0); } while (0)
; #define PG8_LDA(dst, b, h) do { _Pragma("unroll") for (int m = 0; m < 4; ++m) _Pragma("unroll") for (int k = 0; k < 2; ++k) dst[m][k] = *(const PG8_LAS bf16x8*)(lds + PG8_SA(b, h) + aoff + m * 2048 + k * 1024); } while (0)
; #define PG8_LDB(dst, b, h) do { _Pragma("unroll") for (int n = 0; n < 2; ++n) _Pragma("unroll") for (int k = 0; k < 2; ++k) dst[n][k] = *(const PG8_LAS bf16x8*)(lds + PG8_SB(b, h) + boff + n * 2048 + k * 1024); } while (0)
; #define PG8_MMA(ai, bj, At, Bt) do { __builtin_amdgcn_s_setprio(1); _Pragma("unroll") for (int m = 0; m < 4; ++m) _Pragma("unroll") for (int n = 0; n < 2; ++n) _Pragma("unroll") for (int k = 0; k < 2; ++k) \
;         acc[ai][bj][m][n] = __builtin_amdgcn_mfma_f32_16x16x32_bf16(Bt[n][k], At[m][k], acc[ai][bj][m][n], 0, 0, 0); __builtin_amdgcn_s_setprio(0); } while (0)
; template <class Epi, class Sched, bool ALIGN_EPI = false, bool SP2 = false>
; __device__ __forceinline__ void gemm_phase(PG8_LAS unsigned char* lds, const Gemm g, const Sched& S, const Epi& E, const int tid) {
;     ...
;     for (;;) {
;         const bool has_next = S.next(ui + 1, nxt);
;         const char* nA = has_next ? (const char*)g.A + (size_t)nxt.pm * tstep : cA; const char* nB = has_next ? (const char*)g.Bt + (size_t)nxt.pn * tstep : cB;
;         for (int t = 0; t < nt; t += 2) {
;             const bool last = (t == nt - 2);
;             const char* a1 = cA + (size_t)(t + 1) * kstep;
;             const char* a2 = last ? nA : cA + (size_t)(t + 2) * kstep; const char* b2 = last ? nB : cB + (size_t)(t + 2) * kstep;
;             const char* a3 = a2 + kstep; const char* b3 = b2 + kstep;
;             if (last && has_next) S.a_ready(nxt);
;             if constexpr (SP2) {
;             PG8_LDB(B0, 0, 0); PG8_LDB(B1, 0, 1); PG8_SCHED; PG8_LDA(At, 0, 0); PG8_STAGE(PG8_SA(1, 1), a1 + hstep, voffA);
;             PG8_WAIT_V(8); PG8_WAIT_L(0); PG8_BAR; PG8_MMA(0, 0, At, B0); PG8_MMA(0, 1, At, B1); PG8_BAR; PG8_SCHED;
;             PG8_LDA(At, 0, 1); PG8_STAGE(PG8_SB(0, 0), b2, voffB); PG8_STAGE(PG8_SB(0, 1), b2 + hstep, voffB); PG8_STAGE(PG8_SA(0, 0), a2, voffA);
.LBB0_841:
	s_ashr_i32 s13, s12, 31
	s_lshl_b64 s[14:15], s[12:13], 19
	s_add_u32 s14, s34, s14
	s_addc_u32 s15, s36, s15
	s_and_b64 s[16:17], s[38:39], exec
	s_cselect_b32 s13, s15, s23
	s_cselect_b32 s19, s14, s22
	s_ashr_i32 s11, s10, 31
	s_lshl_b64 s[16:17], s[10:11], 19
	s_add_u32 s16, s4, s16
	s_addc_u32 s17, s5, s17
	s_and_b64 s[26:27], s[38:39], exec
	s_cselect_b32 s11, s17, s25
	s_cselect_b32 s46, s16, s24
	s_add_u32 s22, s22, 0x40080
	s_addc_u32 s23, s23, 0
	s_add_u32 s47, s24, 0x100
	v_mov_b32_e32 v4, 0
	s_addc_u32 s48, s25, 0
	s_mov_b32 s49, -2
	s_add_u32 s24, s22, 0xfffc0080
	s_addc_u32 s25, s23, -1
	s_add_i32 s50, 0, 0x10000
	s_cmp_eq_u32 s49, 12
	s_cselect_b32 s27, s13, s25
	s_cselect_b32 s26, s19, s24
	v_add_u32_e32 v148, s50, v146
	s_cselect_b32 s25, s11, s48
	s_cselect_b32 s24, s46, s47
	s_add_i32 s52, 0, 0x14000
	ds_read_b128 v[142:145], v148
	ds_read_b128 v[166:169], v148 offset:1024
	ds_read_b128 v[170:173], v148 offset:2048
	ds_read_b128 v[174:177], v148 offset:3072
	v_add_u32_e32 v148, s52, v146
	ds_read_b128 v[178:181], v148
	ds_read_b128 v[182:185], v148 offset:1024
	ds_read_b128 v[186:189], v148 offset:2048
	ds_read_b128 v[190:193], v148 offset:3072
	v_lshl_add_u64 v[226:227], s[22:23], 0, v[138:139]
	s_add_i32 m0, s21, 0xc000
	ds_read_b128 v[194:197], v153
	ds_read_b128 v[198:201], v153 offset:1024
	ds_read_b128 v[202:205], v153 offset:2048
	ds_read_b128 v[206:209], v153 offset:3072
	ds_read_b128 v[210:213], v153 offset:4096
	ds_read_b128 v[214:217], v153 offset:5120
	ds_read_b128 v[218:221], v153 offset:6144
	ds_read_b128 v[222:225], v153 offset:7168
	global_load_lds_dwordx4 v[226:227], off
	v_lshl_add_u64 v[226:227], s[22:23], 0, v[140:141]
	s_add_i32 m0, s21, 0xe000
	s_nop 0
	global_load_lds_dwordx4 v[226:227], off
	s_waitcnt vmcnt(8)
	s_waitcnt lgkmcnt(0)
	s_barrier
	s_waitcnt lgkmcnt(0)
	v_mfma_f32_16x16x32_bf16 v[128:131], v[142:145], v[194:197], 0
	v_mfma_f32_16x16x32_bf16 v[124:127], v[170:173], v[194:197], 0
	v_mfma_f32_16x16x32_bf16 v[112:115], v[142:145], v[202:205], 0
	v_mfma_f32_16x16x32_bf16 v[108:111], v[170:173], v[202:205], 0
	v_mfma_f32_16x16x32_bf16 v[96:99], v[142:145], v[210:213], 0
	v_mfma_f32_16x16x32_bf16 v[92:95], v[170:173], v[210:213], 0
	v_mfma_f32_16x16x32_bf16 v[80:83], v[142:145], v[218:221], 0
	v_mfma_f32_16x16x32_bf16 v[76:79], v[170:173], v[218:221], 0
	v_mfma_f32_16x16x32_bf16 v[128:131], v[166:169], v[198:201], v[128:131]
	v_mfma_f32_16x16x32_bf16 v[124:127], v[174:177], v[198:201], v[124:127]
	v_mfma_f32_16x16x32_bf16 v[112:115], v[166:169], v[206:209], v[112:115]
	v_mfma_f32_16x16x32_bf16 v[108:111], v[174:177], v[206:209], v[108:111]
	v_mfma_f32_16x16x32_bf16 v[96:99], v[166:169], v[214:217], v[96:99]
	v_mfma_f32_16x16x32_bf16 v[92:95], v[174:177], v[214:217], v[92:95]
	v_mfma_f32_16x16x32_bf16 v[80:83], v[166:169], v[222:225], v[80:83]
	v_mfma_f32_16x16x32_bf16 v[76:79], v[174:177], v[222:225], v[76:79]
	v_mfma_f32_16x16x32_bf16 v[120:123], v[178:181], v[194:197], 0
	v_mfma_f32_16x16x32_bf16 v[116:119], v[186:189], v[194:197], 0
	v_mfma_f32_16x16x32_bf16 v[104:107], v[178:181], v[202:205], 0
	v_mfma_f32_16x16x32_bf16 v[100:103], v[186:189], v[202:205], 0
	v_mfma_f32_16x16x32_bf16 v[88:91], v[178:181], v[210:213], 0
	v_mfma_f32_16x16x32_bf16 v[84:87], v[186:189], v[210:213], 0
	v_mfma_f32_16x16x32_bf16 v[72:75], v[178:181], v[218:221], 0
	v_mfma_f32_16x16x32_bf16 v[68:71], v[186:189], v[218:221], 0
	v_mfma_f32_16x16x32_bf16 v[120:123], v[182:185], v[198:201], v[120:123]
	v_mfma_f32_16x16x32_bf16 v[116:119], v[190:193], v[198:201], v[116:119]
	v_mfma_f32_16x16x32_bf16 v[104:107], v[182:185], v[206:209], v[104:107]
	v_mfma_f32_16x16x32_bf16 v[100:103], v[190:193], v[206:209], v[100:103]
	v_mfma_f32_16x16x32_bf16 v[88:91], v[182:185], v[214:217], v[88:91]
	v_mfma_f32_16x16x32_bf16 v[84:87], v[190:193], v[214:217], v[84:87]
	v_mfma_f32_16x16x32_bf16 v[72:75], v[182:185], v[222:225], v[72:75]
	v_mfma_f32_16x16x32_bf16 v[68:71], v[190:193], v[222:225], v[68:71]
	s_barrier
	s_add_i32 s50, s50, s37
	v_lshl_add_u64 v[226:227], s[24:25], 0, v[132:133]
	s_mov_b32 m0, s50
	ds_read_b128 v[194:197], v153 offset:16384
	ds_read_b128 v[198:201], v153 offset:17408
	ds_read_b128 v[202:205], v153 offset:18432
	ds_read_b128 v[206:209], v153 offset:19456
	ds_read_b128 v[210:213], v153 offset:20480
	ds_read_b128 v[214:217], v153 offset:21504
	ds_read_b128 v[218:221], v153 offset:22528
	ds_read_b128 v[222:225], v153 offset:23552
	global_load_lds_dwordx4 v[226:227], off
	s_add_i32 m0, s50, 0x2000
	s_add_u32 s50, s24, 0x40000
	v_lshl_add_u64 v[238:239], s[24:25], 0, v[136:137]
	s_addc_u32 s51, s25, 0
	s_add_i32 s52, s52, s37
	global_load_lds_dwordx4 v[238:239], off
	v_lshl_add_u64 v[240:241], s[50:51], 0, v[132:133]
	s_mov_b32 m0, s52
	v_lshl_add_u64 v[242:243], s[26:27], 0, v[134:135]
	global_load_lds_dwordx4 v[240:241], off
	v_lshl_add_u64 v[240:241], s[50:51], 0, v[136:137]
	s_add_i32 m0, s52, 0x2000
	s_nop 0
	global_load_lds_dwordx4 v[240:241], off
	v_lshl_add_u64 v[240:241], s[26:27], 0, v[0:1]
	s_mov_b32 m0, s21
	s_nop 0
	global_load_lds_dwordx4 v[240:241], off
	s_mov_b32 m0, s40
	s_nop 0
	global_load_lds_dwordx4 v[242:243], off
	s_waitcnt vmcnt(8)
	s_waitcnt lgkmcnt(0)
	s_barrier
; #define PG8_STAGE(bufoff, gbase, voff) do { _Pragma("unroll") for (int _i = 0; _i < 2; ++_i) \
;         __builtin_amdgcn_global_load_lds((const unsigned*)((const char*)(gbase) + (voff)[_i]), (PG8_LAS unsigned*)(lds + (bufoff) + ldsw + _i * 8192), 16, 0, 0); } while (0)
; #define PG8_LDA(dst, b, h) do { _Pragma("unroll") for (int m = 0; m < 4; ++m) _Pragma("unroll") for (int k = 0; k < 2; ++k) dst[m][k] = *(const PG8_LAS bf16x8*)(lds + PG8_SA(b, h) + aoff + m * 2048 + k * 1024); } while (0)
; #define PG8_LDB(dst, b, h) do { _Pragma("unroll") for (int n = 0; n < 2; ++n) _Pragma("unroll") for (int k = 0; k < 2; ++k) dst[n][k] = *(const PG8_LAS bf16x8*)(lds + PG8_SB(b, h) + boff + n * 2048 + k * 1024); } while (0)
; #define PG8_MMA(ai, bj, At, Bt) do { __builtin_amdgcn_s_setprio(1); _Pragma("unroll") for (int m = 0; m < 4; ++m) _Pragma("unroll") for (int n = 0; n < 2; ++n) _Pragma("unroll") for (int k = 0; k < 2; ++k) \
;         acc[ai][bj][m][n] = __builtin_amdgcn_mfma_f32_16x16x32_bf16(Bt[n][k], At[m][k], acc[ai][bj][m][n], 0, 0, 0); __builtin_amdgcn_s_setprio(0); } while (0)
; #define PG8_WAIT_V(n) asm volatile("s_waitcnt vmcnt(" #n ")" ::: "memory")
; #define PG8_WAIT_L(n) asm volatile("s_waitcnt lgkmcnt(" #n ")" ::: "memory")
; #define PG8_BAR __builtin_amdgcn_s_barrier()
; #define PG8_SCHED __builtin_amdgcn_sched_barrier(0)
; template <class Epi, class Sched, bool ALIGN_EPI = false, bool SP2 = false>
; __device__ __forceinline__ void gemm_phase(PG8_LAS unsigned char* lds, const Gemm g, const Sched& S, const Epi& E, const int tid) {
;     ...
;             PG8_WAIT_V(8); PG8_WAIT_L(0); PG8_BAR; PG8_MMA(1, 0, At, B0); PG8_MMA(1, 1, At, B1); PG8_BAR; PG8_SCHED;
;             PG8_LDB(B0, 1, 0); PG8_LDB(B1, 1, 1); PG8_SCHED; PG8_LDA(At, 1, 0); PG8_STAGE(PG8_SA(0, 1), a2 + hstep, voffA);
;             PG8_WAIT_V(8); PG8_WAIT_L(0); PG8_BAR; PG8_MMA(0, 0, At, B0); PG8_MMA(0, 1, At, B1); PG8_BAR; PG8_SCHED;
	s_waitcnt lgkmcnt(0)
	v_mfma_f32_16x16x32_bf16 v[64:67], v[142:145], v[194:197], 0
	v_mfma_f32_16x16x32_bf16 v[60:63], v[170:173], v[194:197], 0
	v_mfma_f32_16x16x32_bf16 v[48:51], v[142:145], v[202:205], 0
	v_mfma_f32_16x16x32_bf16 v[44:47], v[170:173], v[202:205], 0
	v_mfma_f32_16x16x32_bf16 v[32:35], v[142:145], v[210:213], 0
	v_mfma_f32_16x16x32_bf16 v[28:31], v[170:173], v[210:213], 0
	v_mfma_f32_16x16x32_bf16 v[16:19], v[142:145], v[218:221], 0
	v_mfma_f32_16x16x32_bf16 v[12:15], v[170:173], v[218:221], 0
	v_mfma_f32_16x16x32_bf16 v[64:67], v[166:169], v[198:201], v[64:67]
	v_mfma_f32_16x16x32_bf16 v[60:63], v[174:177], v[198:201], v[60:63]
	v_mfma_f32_16x16x32_bf16 v[48:51], v[166:169], v[206:209], v[48:51]
	v_mfma_f32_16x16x32_bf16 v[44:47], v[174:177], v[206:209], v[44:47]
	v_mfma_f32_16x16x32_bf16 v[32:35], v[166:169], v[214:217], v[32:35]
	v_mfma_f32_16x16x32_bf16 v[28:31], v[174:177], v[214:217], v[28:31]
	v_mfma_f32_16x16x32_bf16 v[16:19], v[166:169], v[222:225], v[16:19]
	v_mfma_f32_16x16x32_bf16 v[12:15], v[174:177], v[222:225], v[12:15]
	v_mfma_f32_16x16x32_bf16 v[56:59], v[178:181], v[194:197], 0
	v_mfma_f32_16x16x32_bf16 v[52:55], v[186:189], v[194:197], 0
	v_mfma_f32_16x16x32_bf16 v[40:43], v[178:181], v[202:205], 0
	v_mfma_f32_16x16x32_bf16 v[36:39], v[186:189], v[202:205], 0
	v_mfma_f32_16x16x32_bf16 v[24:27], v[178:181], v[210:213], 0
	v_mfma_f32_16x16x32_bf16 v[20:23], v[186:189], v[210:213], 0
	v_mfma_f32_16x16x32_bf16 v[8:11], v[178:181], v[218:221], 0
	v_mfma_f32_16x16x32_bf16 v[4:7], v[186:189], v[218:221], 0
	v_mfma_f32_16x16x32_bf16 v[56:59], v[182:185], v[198:201], v[56:59]
	v_mfma_f32_16x16x32_bf16 v[52:55], v[190:193], v[198:201], v[52:55]
	v_mfma_f32_16x16x32_bf16 v[40:43], v[182:185], v[206:209], v[40:43]
	v_mfma_f32_16x16x32_bf16 v[36:39], v[190:193], v[206:209], v[36:39]
	v_mfma_f32_16x16x32_bf16 v[24:27], v[182:185], v[214:217], v[24:27]
	v_mfma_f32_16x16x32_bf16 v[20:23], v[190:193], v[214:217], v[20:23]
	v_mfma_f32_16x16x32_bf16 v[8:11], v[182:185], v[222:225], v[8:11]
	v_mfma_f32_16x16x32_bf16 v[4:7], v[190:193], v[222:225], v[4:7]
	s_barrier
	s_add_i32 s50, 0, 0x18000
	v_add_u32_e32 v148, s50, v146
	s_add_i32 s51, 0, 0x1c000
	ds_read_b128 v[142:145], v148
	ds_read_b128 v[166:169], v148 offset:1024
	ds_read_b128 v[170:173], v148 offset:2048
	ds_read_b128 v[174:177], v148 offset:3072
	v_add_u32_e32 v148, s51, v146
	ds_read_b128 v[178:181], v148
	ds_read_b128 v[182:185], v148 offset:1024
	ds_read_b128 v[186:189], v148 offset:2048
	ds_read_b128 v[190:193], v148 offset:3072
	s_add_u32 s26, s26, 0x40000
	s_addc_u32 s27, s27, 0
	s_mov_b32 m0, s41
	v_lshl_add_u64 v[244:245], s[26:27], 0, v[0:1]
	ds_read_b128 v[194:197], v153 offset:32768
	ds_read_b128 v[198:201], v153 offset:33792
	ds_read_b128 v[202:205], v153 offset:34816
	ds_read_b128 v[206:209], v153 offset:35840
	ds_read_b128 v[210:213], v153 offset:36864
	ds_read_b128 v[214:217], v153 offset:37888
	ds_read_b128 v[218:221], v153 offset:38912
	ds_read_b128 v[222:225], v153 offset:39936
	global_load_lds_dwordx4 v[244:245], off
	v_lshl_add_u64 v[244:245], s[26:27], 0, v[134:135]
	s_mov_b32 m0, s42
	s_nop 0
	global_load_lds_dwordx4 v[244:245], off
	s_waitcnt vmcnt(8)
	s_waitcnt lgkmcnt(0)
	s_barrier
	s_waitcnt lgkmcnt(0)
	v_mfma_f32_16x16x32_bf16 v[128:131], v[142:145], v[194:197], v[128:131]
	v_mfma_f32_16x16x32_bf16 v[124:127], v[170:173], v[194:197], v[124:127]
	v_mfma_f32_16x16x32_bf16 v[112:115], v[142:145], v[202:205], v[112:115]
	v_mfma_f32_16x16x32_bf16 v[108:111], v[170:173], v[202:205], v[108:111]
	v_mfma_f32_16x16x32_bf16 v[96:99], v[142:145], v[210:213], v[96:99]
	v_mfma_f32_16x16x32_bf16 v[92:95], v[170:173], v[210:213], v[92:95]
	v_mfma_f32_16x16x32_bf16 v[80:83], v[142:145], v[218:221], v[80:83]
	v_mfma_f32_16x16x32_bf16 v[76:79], v[170:173], v[218:221], v[76:79]
	v_mfma_f32_16x16x32_bf16 v[128:131], v[166:169], v[198:201], v[128:131]
	v_mfma_f32_16x16x32_bf16 v[124:127], v[174:177], v[198:201], v[124:127]
	v_mfma_f32_16x16x32_bf16 v[112:115], v[166:169], v[206:209], v[112:115]
	v_mfma_f32_16x16x32_bf16 v[108:111], v[174:177], v[206:209], v[108:111]
	v_mfma_f32_16x16x32_bf16 v[96:99], v[166:169], v[214:217], v[96:99]
	v_mfma_f32_16x16x32_bf16 v[92:95], v[174:177], v[214:217], v[92:95]
	v_mfma_f32_16x16x32_bf16 v[80:83], v[166:169], v[222:225], v[80:83]
	v_mfma_f32_16x16x32_bf16 v[76:79], v[174:177], v[222:225], v[76:79]
	v_mfma_f32_16x16x32_bf16 v[120:123], v[178:181], v[194:197], v[120:123]
	v_mfma_f32_16x16x32_bf16 v[116:119], v[186:189], v[194:197], v[116:119]
	v_mfma_f32_16x16x32_bf16 v[104:107], v[178:181], v[202:205], v[104:107]
	v_mfma_f32_16x16x32_bf16 v[100:103], v[186:189], v[202:205], v[100:103]
	v_mfma_f32_16x16x32_bf16 v[88:91], v[178:181], v[210:213], v[88:91]
	v_mfma_f32_16x16x32_bf16 v[84:87], v[186:189], v[210:213], v[84:87]
	v_mfma_f32_16x16x32_bf16 v[72:75], v[178:181], v[218:221], v[72:75]
	v_mfma_f32_16x16x32_bf16 v[68:71], v[186:189], v[218:221], v[68:71]
	v_mfma_f32_16x16x32_bf16 v[120:123], v[182:185], v[198:201], v[120:123]
	v_mfma_f32_16x16x32_bf16 v[116:119], v[190:193], v[198:201], v[116:119]
	v_mfma_f32_16x16x32_bf16 v[104:107], v[182:185], v[206:209], v[104:107]
	v_mfma_f32_16x16x32_bf16 v[100:103], v[190:193], v[206:209], v[100:103]
	v_mfma_f32_16x16x32_bf16 v[88:91], v[182:185], v[214:217], v[88:91]
	v_mfma_f32_16x16x32_bf16 v[84:87], v[190:193], v[214:217], v[84:87]
	v_mfma_f32_16x16x32_bf16 v[72:75], v[182:185], v[222:225], v[72:75]
	v_mfma_f32_16x16x32_bf16 v[68:71], v[190:193], v[222:225], v[68:71]
	s_barrier
; #define PG8_STAGE(bufoff, gbase, voff) do { _Pragma("unroll") for (int _i = 0; _i < 2; ++_i) \
;         __builtin_amdgcn_global_load_lds((const unsigned*)((const char*)(gbase) + (voff)[_i]), (PG8_LAS unsigned*)(lds + (bufoff) + ldsw + _i * 8192), 16, 0, 0); } while (0)
; #define PG8_LDA(dst, b, h) do { _Pragma("unroll") for (int m = 0; m < 4; ++m) _Pragma("unroll") for (int k = 0; k < 2; ++k) dst[m][k] = *(const PG8_LAS bf16x8*)(lds + PG8_SA(b, h) + aoff + m * 2048 + k * 1024); } while (0)
; #define PG8_MMA(ai, bj, At, Bt) do { __builtin_amdgcn_s_setprio(1); _Pragma("unroll") for (int m = 0; m < 4; ++m) _Pragma("unroll") for (int n = 0; n < 2; ++n) _Pragma("unroll") for (int k = 0; k < 2; ++k) \
;         acc[ai][bj][m][n] = __builtin_amdgcn_mfma_f32_16x16x32_bf16(Bt[n][k], At[m][k], acc[ai][bj][m][n], 0, 0, 0); __builtin_amdgcn_s_setprio(0); } while (0)
; #define PG8_WAIT_V(n) asm volatile("s_waitcnt vmcnt(" #n ")" ::: "memory")
; #define PG8_WAIT_L(n) asm volatile("s_waitcnt lgkmcnt(" #n ")" ::: "memory")
; #define PG8_BAR __builtin_amdgcn_s_barrier()
; #define PG8_SCHED __builtin_amdgcn_sched_barrier(0)
; template <class Epi, class Sched, bool ALIGN_EPI = false, bool SP2 = false>
; __device__ __forceinline__ void gemm_phase(PG8_LAS unsigned char* lds, const Gemm g, const Sched& S, const Epi& E, const int tid) {
;     ...
;             PG8_LDA(At, 1, 1); PG8_STAGE(PG8_SB(1, 0), b3, voffB); PG8_STAGE(PG8_SB(1, 1), b3 + hstep, voffB); PG8_STAGE(PG8_SA(1, 0), a3, voffA);
;             PG8_WAIT_V(8); PG8_WAIT_L(0); PG8_BAR; PG8_MMA(1, 0, At, B0); PG8_MMA(1, 1, At, B1); PG8_BAR; PG8_SCHED;
	s_add_i32 s26, s50, s37
	v_lshl_add_u64 v[226:227], v[226:227], 0, s[0:1]
	s_mov_b32 m0, s26
	ds_read_b128 v[194:197], v153 offset:49152
	ds_read_b128 v[198:201], v153 offset:50176
	ds_read_b128 v[202:205], v153 offset:51200
	ds_read_b128 v[206:209], v153 offset:52224
	ds_read_b128 v[210:213], v153 offset:53248
	ds_read_b128 v[214:217], v153 offset:54272
	ds_read_b128 v[218:221], v153 offset:55296
	ds_read_b128 v[222:225], v153 offset:56320
	global_load_lds_dwordx4 v[226:227], off
	s_add_i32 m0, s26, 0x2000
	s_add_u32 s24, s24, 0x40080
	v_lshl_add_u64 v[226:227], v[238:239], 0, s[0:1]
	s_addc_u32 s25, s25, 0
	s_add_i32 s26, s51, s37
	global_load_lds_dwordx4 v[226:227], off
	v_lshl_add_u64 v[226:227], s[24:25], 0, v[132:133]
	s_mov_b32 m0, s26
	s_nop 0
	global_load_lds_dwordx4 v[226:227], off
	v_lshl_add_u64 v[226:227], s[24:25], 0, v[136:137]
	s_add_i32 m0, s26, 0x2000
	s_nop 0
	global_load_lds_dwordx4 v[226:227], off
	v_lshl_add_u64 v[226:227], v[240:241], 0, s[0:1]
	s_mov_b32 m0, s43
	s_nop 0
	global_load_lds_dwordx4 v[226:227], off
	v_lshl_add_u64 v[226:227], v[242:243], 0, s[0:1]
	s_mov_b32 m0, s44
	s_nop 0
	global_load_lds_dwordx4 v[226:227], off
	s_waitcnt vmcnt(8)
	s_waitcnt lgkmcnt(0)
	s_barrier
	s_waitcnt lgkmcnt(0)
	v_mfma_f32_16x16x32_bf16 v[64:67], v[142:145], v[194:197], v[64:67]
	v_mfma_f32_16x16x32_bf16 v[60:63], v[170:173], v[194:197], v[60:63]
	v_mfma_f32_16x16x32_bf16 v[48:51], v[142:145], v[202:205], v[48:51]
	v_mfma_f32_16x16x32_bf16 v[44:47], v[170:173], v[202:205], v[44:47]
	v_mfma_f32_16x16x32_bf16 v[32:35], v[142:145], v[210:213], v[32:35]
	v_mfma_f32_16x16x32_bf16 v[28:31], v[170:173], v[210:213], v[28:31]
	v_mfma_f32_16x16x32_bf16 v[16:19], v[142:145], v[218:221], v[16:19]
	v_mfma_f32_16x16x32_bf16 v[12:15], v[170:173], v[218:221], v[12:15]
	v_mfma_f32_16x16x32_bf16 v[64:67], v[166:169], v[198:201], v[64:67]
	v_mfma_f32_16x16x32_bf16 v[60:63], v[174:177], v[198:201], v[60:63]
	v_mfma_f32_16x16x32_bf16 v[48:51], v[166:169], v[206:209], v[48:51]
	v_mfma_f32_16x16x32_bf16 v[44:47], v[174:177], v[206:209], v[44:47]
	v_mfma_f32_16x16x32_bf16 v[32:35], v[166:169], v[214:217], v[32:35]
	v_mfma_f32_16x16x32_bf16 v[28:31], v[174:177], v[214:217], v[28:31]
	v_mfma_f32_16x16x32_bf16 v[16:19], v[166:169], v[222:225], v[16:19]
	v_mfma_f32_16x16x32_bf16 v[12:15], v[174:177], v[222:225], v[12:15]
	v_mfma_f32_16x16x32_bf16 v[56:59], v[178:181], v[194:197], v[56:59]
	v_mfma_f32_16x16x32_bf16 v[52:55], v[186:189], v[194:197], v[52:55]
	v_mfma_f32_16x16x32_bf16 v[40:43], v[178:181], v[202:205], v[40:43]
	v_mfma_f32_16x16x32_bf16 v[36:39], v[186:189], v[202:205], v[36:39]
	v_mfma_f32_16x16x32_bf16 v[24:27], v[178:181], v[210:213], v[24:27]
	v_mfma_f32_16x16x32_bf16 v[20:23], v[186:189], v[210:213], v[20:23]
	v_mfma_f32_16x16x32_bf16 v[8:11], v[178:181], v[218:221], v[8:11]
	v_mfma_f32_16x16x32_bf16 v[4:7], v[186:189], v[218:221], v[4:7]
	v_mfma_f32_16x16x32_bf16 v[56:59], v[182:185], v[198:201], v[56:59]
	v_mfma_f32_16x16x32_bf16 v[52:55], v[190:193], v[198:201], v[52:55]
	v_mfma_f32_16x16x32_bf16 v[40:43], v[182:185], v[206:209], v[40:43]
	v_mfma_f32_16x16x32_bf16 v[36:39], v[190:193], v[206:209], v[36:39]
	v_mfma_f32_16x16x32_bf16 v[24:27], v[182:185], v[214:217], v[24:27]
	v_mfma_f32_16x16x32_bf16 v[20:23], v[190:193], v[214:217], v[20:23]
	v_mfma_f32_16x16x32_bf16 v[8:11], v[182:185], v[222:225], v[8:11]
	v_mfma_f32_16x16x32_bf16 v[4:7], v[190:193], v[222:225], v[4:7]
	s_barrier
	s_add_i32 s49, s49, 2
	s_add_u32 s22, s22, 0x100
	s_addc_u32 s23, s23, 0
	s_add_u32 s47, s47, 0x100
	s_addc_u32 s48, s48, 0
	s_cmp_gt_u32 s49, 13
	s_cbranch_scc0 .LBB0_842
	s_branch .Lpeel_exit4
	.p2align	6
